# code placement: all 14 GEMM k-loop heads aligned to 64 bytes (.p2align 6)
# speedup vs baseline: 1.0025x; 1.0025x over previous
; template <class Epi, bool ALIGN_EPI = PG8_ALIGN>
; __device__ __forceinline__ void gemm_phase(LAS unsigned char* lds, const Gemm g, const StaticOrder S, const Epi E) {
;     ...
;         const bool has_next = S.next(ui + 1, nxt);
;         const char* nA = has_next ? (const char*)g.A + (size_t)nxt.pm * tstepA : cA; const char* nB = has_next ? (const char*)g.Bt + (size_t)nxt.pn * tstepB : cB;
;         for (int t = 0; t < nt; t += 2) {
;             const bool last = (t == nt - 2);
;             const char* a1 = cA + (size_t)(t + 1) * kstep;
;             const char* a2 = last ? nA : cA + (size_t)(t + 2) * kstep; const char* b2 = last ? nB : cB + (size_t)(t + 2) * kstep;
;             const char* a3 = a2 + kstep; const char* b3 = b2 + kstep;
;     ...
; #pragma unroll
;         for (int a = 0; a < 2; ++a)
; #pragma unroll
;             for (int b = 0; b < 2; ++b)
; #pragma unroll
;                 for (int m = 0; m < 4; ++m)
; #pragma unroll
;                     for (int n = 0; n < 2; ++n) acc[a][b][m][n] = (f32x4){0.f, 0.f, 0.f, 0.f};
;         cur = nxt; cA = nA; cB = nB; ++ui;
.LBB0_334:
	s_ashr_i32 s43, s42, 31
	s_lshl_b64 s[46:47], s[42:43], 20
	s_add_u32 s46, s40, s46
	s_addc_u32 s47, s41, s47
	s_and_b64 s[48:49], s[2:3], exec
	s_cselect_b32 s14, s47, s51
	s_cselect_b32 s35, s46, s50
	s_ashr_i32 s11, s10, 31
	s_lshl_b64 s[48:49], s[10:11], 20
	s_add_u32 s48, s86, s48
	s_addc_u32 s49, s87, s49
	s_and_b64 s[60:61], s[2:3], exec
	s_cselect_b32 s11, s49, s59
	s_cselect_b32 s43, s48, s58
	s_add_u32 s50, s50, 0x80080
	s_addc_u32 s51, s51, 0
	s_add_u32 s72, s58, 0x100
	v_mov_b32_e32 v0, 0
	s_addc_u32 s73, s59, 0
	s_mov_b32 s74, -2
	v_mov_b32_e32 v1, v0
	v_mov_b32_e32 v2, v0
	v_mov_b32_e32 v3, v0
	v_mov_b32_e32 v8, v0
	v_mov_b32_e32 v9, v0
	v_mov_b32_e32 v10, v0
	v_mov_b32_e32 v11, v0
	v_mov_b32_e32 v16, v0
	v_mov_b32_e32 v17, v0
	v_mov_b32_e32 v18, v0
	v_mov_b32_e32 v19, v0
	v_mov_b32_e32 v24, v0
	v_mov_b32_e32 v25, v0
	v_mov_b32_e32 v26, v0
	v_mov_b32_e32 v27, v0
	v_mov_b32_e32 v32, v0
	v_mov_b32_e32 v33, v0
	v_mov_b32_e32 v34, v0
	v_mov_b32_e32 v35, v0
	v_mov_b32_e32 v40, v0
	v_mov_b32_e32 v41, v0
	v_mov_b32_e32 v42, v0
	v_mov_b32_e32 v43, v0
	v_mov_b32_e32 v48, v0
	v_mov_b32_e32 v49, v0
	v_mov_b32_e32 v50, v0
	v_mov_b32_e32 v51, v0
	v_mov_b32_e32 v56, v0
	v_mov_b32_e32 v57, v0
	v_mov_b32_e32 v58, v0
	v_mov_b32_e32 v59, v0
	v_mov_b32_e32 v4, v0
	v_mov_b32_e32 v5, v0
	v_mov_b32_e32 v6, v0
	v_mov_b32_e32 v7, v0
	v_mov_b32_e32 v12, v0
	v_mov_b32_e32 v13, v0
	v_mov_b32_e32 v14, v0
	v_mov_b32_e32 v15, v0
	v_mov_b32_e32 v20, v0
	v_mov_b32_e32 v21, v0
	v_mov_b32_e32 v22, v0
	v_mov_b32_e32 v23, v0
	v_mov_b32_e32 v28, v0
	v_mov_b32_e32 v29, v0
	v_mov_b32_e32 v30, v0
	v_mov_b32_e32 v31, v0
	v_mov_b32_e32 v36, v0
	v_mov_b32_e32 v37, v0
	v_mov_b32_e32 v38, v0
	v_mov_b32_e32 v39, v0
	v_mov_b32_e32 v44, v0
	v_mov_b32_e32 v45, v0
	v_mov_b32_e32 v46, v0
	v_mov_b32_e32 v47, v0
	v_mov_b32_e32 v52, v0
	v_mov_b32_e32 v53, v0
	v_mov_b32_e32 v54, v0
	v_mov_b32_e32 v55, v0
	v_mov_b32_e32 v60, v0
	v_mov_b32_e32 v61, v0
	v_mov_b32_e32 v62, v0
	v_mov_b32_e32 v63, v0
	v_mov_b32_e32 v64, v0
	v_mov_b32_e32 v65, v0
	v_mov_b32_e32 v66, v0
	v_mov_b32_e32 v67, v0
	v_mov_b32_e32 v72, v0
	v_mov_b32_e32 v73, v0
	v_mov_b32_e32 v74, v0
	v_mov_b32_e32 v75, v0
	v_mov_b32_e32 v80, v0
	v_mov_b32_e32 v81, v0
	v_mov_b32_e32 v82, v0
	v_mov_b32_e32 v83, v0
	v_mov_b32_e32 v88, v0
	v_mov_b32_e32 v89, v0
	v_mov_b32_e32 v90, v0
	v_mov_b32_e32 v91, v0
	v_mov_b32_e32 v96, v0
	v_mov_b32_e32 v97, v0
	v_mov_b32_e32 v98, v0
	v_mov_b32_e32 v99, v0
	v_mov_b32_e32 v104, v0
	v_mov_b32_e32 v105, v0
	v_mov_b32_e32 v106, v0
	v_mov_b32_e32 v107, v0
	v_mov_b32_e32 v112, v0
	v_mov_b32_e32 v113, v0
	v_mov_b32_e32 v114, v0
	v_mov_b32_e32 v115, v0
	v_mov_b32_e32 v120, v0
	v_mov_b32_e32 v121, v0
	v_mov_b32_e32 v122, v0
	v_mov_b32_e32 v123, v0
	v_mov_b32_e32 v68, v0
	v_mov_b32_e32 v69, v0
	v_mov_b32_e32 v70, v0
	v_mov_b32_e32 v71, v0
	v_mov_b32_e32 v76, v0
	v_mov_b32_e32 v77, v0
	v_mov_b32_e32 v78, v0
	v_mov_b32_e32 v79, v0
	v_mov_b32_e32 v84, v0
	v_mov_b32_e32 v85, v0
	v_mov_b32_e32 v86, v0
	v_mov_b32_e32 v87, v0
	v_mov_b32_e32 v92, v0
	v_mov_b32_e32 v93, v0
	v_mov_b32_e32 v94, v0
	v_mov_b32_e32 v95, v0
	v_mov_b32_e32 v100, v0
	v_mov_b32_e32 v101, v0
	v_mov_b32_e32 v102, v0
	v_mov_b32_e32 v103, v0
	v_mov_b32_e32 v108, v0
	v_mov_b32_e32 v109, v0
	v_mov_b32_e32 v110, v0
	v_mov_b32_e32 v111, v0
	v_mov_b32_e32 v116, v0
	v_mov_b32_e32 v117, v0
	v_mov_b32_e32 v118, v0
	v_mov_b32_e32 v119, v0
	v_mov_b32_e32 v124, v0
	v_mov_b32_e32 v125, v0
	v_mov_b32_e32 v126, v0
	v_mov_b32_e32 v127, v0
	.p2align 6

; template <class Epi, bool ALIGN_EPI = PG8_ALIGN>
; __device__ __forceinline__ void gemm_phase(LAS unsigned char* lds, const Gemm g, const StaticOrder S, const Epi E) {
;     ...
;         const bool has_next = S.next(ui + 1, nxt);
;         const char* nA = has_next ? (const char*)g.A + (size_t)nxt.pm * tstepA : cA; const char* nB = has_next ? (const char*)g.Bt + (size_t)nxt.pn * tstepB : cB;
;         for (int t = 0; t < nt; t += 2) {
;             const bool last = (t == nt - 2);
;             const char* a1 = cA + (size_t)(t + 1) * kstep;
;             const char* a2 = last ? nA : cA + (size_t)(t + 2) * kstep; const char* b2 = last ? nB : cB + (size_t)(t + 2) * kstep;
;             const char* a3 = a2 + kstep; const char* b3 = b2 + kstep;
;     ...
; #pragma unroll
;         for (int a = 0; a < 2; ++a)
; #pragma unroll
;             for (int b = 0; b < 2; ++b)
; #pragma unroll
;                 for (int m = 0; m < 4; ++m)
; #pragma unroll
;                     for (int n = 0; n < 2; ++n) acc[a][b][m][n] = (f32x4){0.f, 0.f, 0.f, 0.f};
;         cur = nxt; cA = nA; cB = nB; ++ui;
.LBB0_419:
	s_add_u32 s12, s12, 0x160080
	s_addc_u32 s13, s13, 0
	s_add_u32 s17, s48, 0x100
	v_mov_b32_e32 v0, 0
	s_addc_u32 s33, s49, 0
	s_mov_b32 s34, -2
	v_mov_b32_e32 v1, v0
	v_mov_b32_e32 v2, v0
	v_mov_b32_e32 v3, v0
	v_mov_b32_e32 v4, v0
	v_mov_b32_e32 v5, v0
	v_mov_b32_e32 v6, v0
	v_mov_b32_e32 v7, v0
	v_mov_b32_e32 v16, v0
	v_mov_b32_e32 v17, v0
	v_mov_b32_e32 v18, v0
	v_mov_b32_e32 v19, v0
	v_mov_b32_e32 v20, v0
	v_mov_b32_e32 v21, v0
	v_mov_b32_e32 v22, v0
	v_mov_b32_e32 v23, v0
	v_mov_b32_e32 v32, v0
	v_mov_b32_e32 v33, v0
	v_mov_b32_e32 v34, v0
	v_mov_b32_e32 v35, v0
	v_mov_b32_e32 v36, v0
	v_mov_b32_e32 v37, v0
	v_mov_b32_e32 v38, v0
	v_mov_b32_e32 v39, v0
	v_mov_b32_e32 v48, v0
	v_mov_b32_e32 v49, v0
	v_mov_b32_e32 v50, v0
	v_mov_b32_e32 v51, v0
	v_mov_b32_e32 v52, v0
	v_mov_b32_e32 v53, v0
	v_mov_b32_e32 v54, v0
	v_mov_b32_e32 v55, v0
	v_mov_b32_e32 v8, v0
	v_mov_b32_e32 v9, v0
	v_mov_b32_e32 v10, v0
	v_mov_b32_e32 v11, v0
	v_mov_b32_e32 v12, v0
	v_mov_b32_e32 v13, v0
	v_mov_b32_e32 v14, v0
	v_mov_b32_e32 v15, v0
	v_mov_b32_e32 v24, v0
	v_mov_b32_e32 v25, v0
	v_mov_b32_e32 v26, v0
	v_mov_b32_e32 v27, v0
	v_mov_b32_e32 v28, v0
	v_mov_b32_e32 v29, v0
	v_mov_b32_e32 v30, v0
	v_mov_b32_e32 v31, v0
	v_mov_b32_e32 v40, v0
	v_mov_b32_e32 v41, v0
	v_mov_b32_e32 v42, v0
	v_mov_b32_e32 v43, v0
	v_mov_b32_e32 v44, v0
	v_mov_b32_e32 v45, v0
	v_mov_b32_e32 v46, v0
	v_mov_b32_e32 v47, v0
	v_mov_b32_e32 v56, v0
	v_mov_b32_e32 v57, v0
	v_mov_b32_e32 v58, v0
	v_mov_b32_e32 v59, v0
	v_mov_b32_e32 v60, v0
	v_mov_b32_e32 v61, v0
	v_mov_b32_e32 v62, v0
	v_mov_b32_e32 v63, v0
	v_mov_b32_e32 v64, v0
	v_mov_b32_e32 v65, v0
	v_mov_b32_e32 v66, v0
	v_mov_b32_e32 v67, v0
	v_mov_b32_e32 v68, v0
	v_mov_b32_e32 v69, v0
	v_mov_b32_e32 v70, v0
	v_mov_b32_e32 v71, v0
	v_mov_b32_e32 v80, v0
	v_mov_b32_e32 v81, v0
	v_mov_b32_e32 v82, v0
	v_mov_b32_e32 v83, v0
	v_mov_b32_e32 v84, v0
	v_mov_b32_e32 v85, v0
	v_mov_b32_e32 v86, v0
	v_mov_b32_e32 v87, v0
	v_mov_b32_e32 v96, v0
	v_mov_b32_e32 v97, v0
	v_mov_b32_e32 v98, v0
	v_mov_b32_e32 v99, v0
	v_mov_b32_e32 v100, v0
	v_mov_b32_e32 v101, v0
	v_mov_b32_e32 v102, v0
	v_mov_b32_e32 v103, v0
	v_mov_b32_e32 v112, v0
	v_mov_b32_e32 v113, v0
	v_mov_b32_e32 v114, v0
	v_mov_b32_e32 v115, v0
	v_mov_b32_e32 v116, v0
	v_mov_b32_e32 v117, v0
	v_mov_b32_e32 v118, v0
	v_mov_b32_e32 v119, v0
	v_mov_b32_e32 v72, v0
	v_mov_b32_e32 v73, v0
	v_mov_b32_e32 v74, v0
	v_mov_b32_e32 v75, v0
	v_mov_b32_e32 v76, v0
	v_mov_b32_e32 v77, v0
	v_mov_b32_e32 v78, v0
	v_mov_b32_e32 v79, v0
	v_mov_b32_e32 v88, v0
	v_mov_b32_e32 v89, v0
	v_mov_b32_e32 v90, v0
	v_mov_b32_e32 v91, v0
	v_mov_b32_e32 v92, v0
	v_mov_b32_e32 v93, v0
	v_mov_b32_e32 v94, v0
	v_mov_b32_e32 v95, v0
	v_mov_b32_e32 v104, v0
	v_mov_b32_e32 v105, v0
	v_mov_b32_e32 v106, v0
	v_mov_b32_e32 v107, v0
	v_mov_b32_e32 v108, v0
	v_mov_b32_e32 v109, v0
	v_mov_b32_e32 v110, v0
	v_mov_b32_e32 v111, v0
	v_mov_b32_e32 v120, v0
	v_mov_b32_e32 v121, v0
	v_mov_b32_e32 v122, v0
	v_mov_b32_e32 v123, v0
	v_mov_b32_e32 v124, v0
	v_mov_b32_e32 v125, v0
	v_mov_b32_e32 v126, v0
	v_mov_b32_e32 v127, v0
	.p2align 6

; template <class Epi, bool ALIGN_EPI = PG8_ALIGN>
; __device__ __forceinline__ void gemm_phase(LAS unsigned char* lds, const Gemm g, const StaticOrder S, const Epi E) {
;     ...
;         const bool has_next = S.next(ui + 1, nxt);
;         const char* nA = has_next ? (const char*)g.A + (size_t)nxt.pm * tstepA : cA; const char* nB = has_next ? (const char*)g.Bt + (size_t)nxt.pn * tstepB : cB;
;         for (int t = 0; t < nt; t += 2) {
;             const bool last = (t == nt - 2);
;             const char* a1 = cA + (size_t)(t + 1) * kstep;
;             const char* a2 = last ? nA : cA + (size_t)(t + 2) * kstep; const char* b2 = last ? nB : cB + (size_t)(t + 2) * kstep;
;             const char* a3 = a2 + kstep; const char* b3 = b2 + kstep;
;     ...
; #pragma unroll
;         for (int a = 0; a < 2; ++a)
; #pragma unroll
;             for (int b = 0; b < 2; ++b)
; #pragma unroll
;                 for (int m = 0; m < 4; ++m)
; #pragma unroll
;                     for (int n = 0; n < 2; ++n) acc[a][b][m][n] = (f32x4){0.f, 0.f, 0.f, 0.f};
;         cur = nxt; cA = nA; cB = nB; ++ui;
.LBB0_506:
	s_ashr_i32 s47, s46, 31
	s_waitcnt lgkmcnt(0)
	s_lshl_b64 s[16:17], s[46:47], 20
	s_add_u32 s48, s40, s16
	s_addc_u32 s49, s41, s17
	s_and_b64 s[16:17], s[2:3], exec
	s_cselect_b32 s14, s49, s53
	s_cselect_b32 s16, s48, s52
	s_ashr_i32 s11, s10, 31
	s_lshl_b64 s[34:35], s[10:11], 20
	s_add_u32 s50, s81, s34
	s_addc_u32 s51, s82, s35
	s_and_b64 s[34:35], s[2:3], exec
	s_cselect_b32 s11, s51, s59
	s_cselect_b32 s17, s50, s58
	s_add_u32 s52, s52, 0x80080
	s_addc_u32 s53, s53, 0
	s_add_u32 s33, s58, 0x100
	v_mov_b32_e32 v0, 0
	s_addc_u32 s34, s59, 0
	s_mov_b32 s35, -2
	v_mov_b32_e32 v1, v0
	v_mov_b32_e32 v2, v0
	v_mov_b32_e32 v3, v0
	v_mov_b32_e32 v4, v0
	v_mov_b32_e32 v5, v0
	v_mov_b32_e32 v6, v0
	v_mov_b32_e32 v7, v0
	v_mov_b32_e32 v8, v0
	v_mov_b32_e32 v9, v0
	v_mov_b32_e32 v10, v0
	v_mov_b32_e32 v11, v0
	v_mov_b32_e32 v12, v0
	v_mov_b32_e32 v13, v0
	v_mov_b32_e32 v14, v0
	v_mov_b32_e32 v15, v0
	v_mov_b32_e32 v16, v0
	v_mov_b32_e32 v17, v0
	v_mov_b32_e32 v18, v0
	v_mov_b32_e32 v19, v0
	v_mov_b32_e32 v20, v0
	v_mov_b32_e32 v21, v0
	v_mov_b32_e32 v22, v0
	v_mov_b32_e32 v23, v0
	v_mov_b32_e32 v24, v0
	v_mov_b32_e32 v25, v0
	v_mov_b32_e32 v26, v0
	v_mov_b32_e32 v27, v0
	v_mov_b32_e32 v28, v0
	v_mov_b32_e32 v29, v0
	v_mov_b32_e32 v30, v0
	v_mov_b32_e32 v31, v0
	v_mov_b32_e32 v64, v0
	v_mov_b32_e32 v65, v0
	v_mov_b32_e32 v66, v0
	v_mov_b32_e32 v67, v0
	v_mov_b32_e32 v68, v0
	v_mov_b32_e32 v69, v0
	v_mov_b32_e32 v70, v0
	v_mov_b32_e32 v71, v0
	v_mov_b32_e32 v72, v0
	v_mov_b32_e32 v73, v0
	v_mov_b32_e32 v74, v0
	v_mov_b32_e32 v75, v0
	v_mov_b32_e32 v76, v0
	v_mov_b32_e32 v77, v0
	v_mov_b32_e32 v78, v0
	v_mov_b32_e32 v79, v0
	v_mov_b32_e32 v80, v0
	v_mov_b32_e32 v81, v0
	v_mov_b32_e32 v82, v0
	v_mov_b32_e32 v83, v0
	v_mov_b32_e32 v84, v0
	v_mov_b32_e32 v85, v0
	v_mov_b32_e32 v86, v0
	v_mov_b32_e32 v87, v0
	v_mov_b32_e32 v88, v0
	v_mov_b32_e32 v89, v0
	v_mov_b32_e32 v90, v0
	v_mov_b32_e32 v91, v0
	v_mov_b32_e32 v92, v0
	v_mov_b32_e32 v93, v0
	v_mov_b32_e32 v94, v0
	v_mov_b32_e32 v95, v0
	v_mov_b32_e32 v32, v0
	v_mov_b32_e32 v33, v0
	v_mov_b32_e32 v34, v0
	v_mov_b32_e32 v35, v0
	v_mov_b32_e32 v36, v0
	v_mov_b32_e32 v37, v0
	v_mov_b32_e32 v38, v0
	v_mov_b32_e32 v39, v0
	v_mov_b32_e32 v40, v0
	v_mov_b32_e32 v41, v0
	v_mov_b32_e32 v42, v0
	v_mov_b32_e32 v43, v0
	v_mov_b32_e32 v44, v0
	v_mov_b32_e32 v45, v0
	v_mov_b32_e32 v46, v0
	v_mov_b32_e32 v47, v0
	v_mov_b32_e32 v48, v0
	v_mov_b32_e32 v49, v0
	v_mov_b32_e32 v50, v0
	v_mov_b32_e32 v51, v0
	v_mov_b32_e32 v52, v0
	v_mov_b32_e32 v53, v0
	v_mov_b32_e32 v54, v0
	v_mov_b32_e32 v55, v0
	v_mov_b32_e32 v56, v0
	v_mov_b32_e32 v57, v0
	v_mov_b32_e32 v58, v0
	v_mov_b32_e32 v59, v0
	v_mov_b32_e32 v60, v0
	v_mov_b32_e32 v61, v0
	v_mov_b32_e32 v62, v0
	v_mov_b32_e32 v63, v0
	v_mov_b32_e32 v96, v0
	v_mov_b32_e32 v97, v0
	v_mov_b32_e32 v98, v0
	v_mov_b32_e32 v99, v0
	v_mov_b32_e32 v100, v0
	v_mov_b32_e32 v101, v0
	v_mov_b32_e32 v102, v0
	v_mov_b32_e32 v103, v0
	v_mov_b32_e32 v104, v0
	v_mov_b32_e32 v105, v0
	v_mov_b32_e32 v106, v0
	v_mov_b32_e32 v107, v0
	v_mov_b32_e32 v108, v0
	v_mov_b32_e32 v109, v0
	v_mov_b32_e32 v110, v0
	v_mov_b32_e32 v111, v0
	v_mov_b32_e32 v112, v0
	v_mov_b32_e32 v113, v0
	v_mov_b32_e32 v114, v0
	v_mov_b32_e32 v115, v0
	v_mov_b32_e32 v116, v0
	v_mov_b32_e32 v117, v0
	v_mov_b32_e32 v118, v0
	v_mov_b32_e32 v119, v0
	v_mov_b32_e32 v120, v0
	v_mov_b32_e32 v121, v0
	v_mov_b32_e32 v122, v0
	v_mov_b32_e32 v123, v0
	v_mov_b32_e32 v124, v0
	v_mov_b32_e32 v125, v0
	v_mov_b32_e32 v126, v0
	v_mov_b32_e32 v127, v0
	.p2align 6

; template <class Epi, bool ALIGN_EPI = PG8_ALIGN>
; __device__ __forceinline__ void gemm_phase(LAS unsigned char* lds, const Gemm g, const StaticOrder S, const Epi E) {
;     ...
;         const bool has_next = S.next(ui + 1, nxt);
;         const char* nA = has_next ? (const char*)g.A + (size_t)nxt.pm * tstepA : cA; const char* nB = has_next ? (const char*)g.Bt + (size_t)nxt.pn * tstepB : cB;
;         for (int t = 0; t < nt; t += 2) {
;             const bool last = (t == nt - 2);
;             const char* a1 = cA + (size_t)(t + 1) * kstep;
;             const char* a2 = last ? nA : cA + (size_t)(t + 2) * kstep; const char* b2 = last ? nB : cB + (size_t)(t + 2) * kstep;
;             const char* a3 = a2 + kstep; const char* b3 = b2 + kstep;
;     ...
; #pragma unroll
;         for (int a = 0; a < 2; ++a)
; #pragma unroll
;             for (int b = 0; b < 2; ++b)
; #pragma unroll
;                 for (int m = 0; m < 4; ++m)
; #pragma unroll
;                     for (int n = 0; n < 2; ++n) acc[a][b][m][n] = (f32x4){0.f, 0.f, 0.f, 0.f};
;         cur = nxt; cA = nA; cB = nB; ++ui;
.LBB0_530:
	s_ashr_i32 s59, s58, 31
	s_lshl_b64 s[42:43], s[58:59], 20
	s_add_u32 s60, s16, s42
	s_addc_u32 s61, s17, s43
	s_and_b64 s[42:43], s[2:3], exec
	s_cselect_b32 s14, s61, s13
	s_cselect_b32 s59, s60, s12
	s_ashr_i32 s53, s52, 31
	s_lshl_b64 s[42:43], s[52:53], 20
	s_add_u32 s62, s40, s42
	s_addc_u32 s63, s41, s43
	s_and_b64 s[42:43], s[2:3], exec
	s_cselect_b32 s53, s63, s65
	s_cselect_b32 s93, s62, s64
	s_add_u32 s12, s12, 0x80080
	s_addc_u32 s13, s13, 0
	s_add_u32 s95, s64, 0x100
	v_mov_b32_e32 v0, 0
	s_addc_u32 s97, s65, 0
	s_mov_b32 vcc_lo, -2
	v_mov_b32_e32 v1, v0
	v_mov_b32_e32 v2, v0
	v_mov_b32_e32 v3, v0
	v_mov_b32_e32 v4, v0
	v_mov_b32_e32 v5, v0
	v_mov_b32_e32 v6, v0
	v_mov_b32_e32 v7, v0
	v_mov_b32_e32 v8, v0
	v_mov_b32_e32 v9, v0
	v_mov_b32_e32 v10, v0
	v_mov_b32_e32 v11, v0
	v_mov_b32_e32 v12, v0
	v_mov_b32_e32 v13, v0
	v_mov_b32_e32 v14, v0
	v_mov_b32_e32 v15, v0
	v_mov_b32_e32 v16, v0
	v_mov_b32_e32 v17, v0
	v_mov_b32_e32 v18, v0
	v_mov_b32_e32 v19, v0
	v_mov_b32_e32 v20, v0
	v_mov_b32_e32 v21, v0
	v_mov_b32_e32 v22, v0
	v_mov_b32_e32 v23, v0
	v_mov_b32_e32 v24, v0
	v_mov_b32_e32 v25, v0
	v_mov_b32_e32 v26, v0
	v_mov_b32_e32 v27, v0
	v_mov_b32_e32 v28, v0
	v_mov_b32_e32 v29, v0
	v_mov_b32_e32 v30, v0
	v_mov_b32_e32 v31, v0
	v_mov_b32_e32 v64, v0
	v_mov_b32_e32 v65, v0
	v_mov_b32_e32 v66, v0
	v_mov_b32_e32 v67, v0
	v_mov_b32_e32 v68, v0
	v_mov_b32_e32 v69, v0
	v_mov_b32_e32 v70, v0
	v_mov_b32_e32 v71, v0
	v_mov_b32_e32 v72, v0
	v_mov_b32_e32 v73, v0
	v_mov_b32_e32 v74, v0
	v_mov_b32_e32 v75, v0
	v_mov_b32_e32 v76, v0
	v_mov_b32_e32 v77, v0
	v_mov_b32_e32 v78, v0
	v_mov_b32_e32 v79, v0
	v_mov_b32_e32 v80, v0
	v_mov_b32_e32 v81, v0
	v_mov_b32_e32 v82, v0
	v_mov_b32_e32 v83, v0
	v_mov_b32_e32 v84, v0
	v_mov_b32_e32 v85, v0
	v_mov_b32_e32 v86, v0
	v_mov_b32_e32 v87, v0
	v_mov_b32_e32 v88, v0
	v_mov_b32_e32 v89, v0
	v_mov_b32_e32 v90, v0
	v_mov_b32_e32 v91, v0
	v_mov_b32_e32 v92, v0
	v_mov_b32_e32 v93, v0
	v_mov_b32_e32 v94, v0
	v_mov_b32_e32 v95, v0
	v_mov_b32_e32 v32, v0
	v_mov_b32_e32 v33, v0
	v_mov_b32_e32 v34, v0
	v_mov_b32_e32 v35, v0
	v_mov_b32_e32 v36, v0
	v_mov_b32_e32 v37, v0
	v_mov_b32_e32 v38, v0
	v_mov_b32_e32 v39, v0
	v_mov_b32_e32 v40, v0
	v_mov_b32_e32 v41, v0
	v_mov_b32_e32 v42, v0
	v_mov_b32_e32 v43, v0
	v_mov_b32_e32 v44, v0
	v_mov_b32_e32 v45, v0
	v_mov_b32_e32 v46, v0
	v_mov_b32_e32 v47, v0
	v_mov_b32_e32 v48, v0
	v_mov_b32_e32 v49, v0
	v_mov_b32_e32 v50, v0
	v_mov_b32_e32 v51, v0
	v_mov_b32_e32 v52, v0
	v_mov_b32_e32 v53, v0
	v_mov_b32_e32 v54, v0
	v_mov_b32_e32 v55, v0
	v_mov_b32_e32 v56, v0
	v_mov_b32_e32 v57, v0
	v_mov_b32_e32 v58, v0
	v_mov_b32_e32 v59, v0
	v_mov_b32_e32 v60, v0
	v_mov_b32_e32 v61, v0
	v_mov_b32_e32 v62, v0
	v_mov_b32_e32 v63, v0
	v_mov_b32_e32 v96, v0
	v_mov_b32_e32 v97, v0
	v_mov_b32_e32 v98, v0
	v_mov_b32_e32 v99, v0
	v_mov_b32_e32 v100, v0
	v_mov_b32_e32 v101, v0
	v_mov_b32_e32 v102, v0
	v_mov_b32_e32 v103, v0
	v_mov_b32_e32 v104, v0
	v_mov_b32_e32 v105, v0
	v_mov_b32_e32 v106, v0
	v_mov_b32_e32 v107, v0
	v_mov_b32_e32 v108, v0
	v_mov_b32_e32 v109, v0
	v_mov_b32_e32 v110, v0
	v_mov_b32_e32 v111, v0
	v_mov_b32_e32 v112, v0
	v_mov_b32_e32 v113, v0
	v_mov_b32_e32 v114, v0
	v_mov_b32_e32 v115, v0
	v_mov_b32_e32 v116, v0
	v_mov_b32_e32 v117, v0
	v_mov_b32_e32 v118, v0
	v_mov_b32_e32 v119, v0
	v_mov_b32_e32 v120, v0
	v_mov_b32_e32 v121, v0
	v_mov_b32_e32 v122, v0
	v_mov_b32_e32 v123, v0
	v_mov_b32_e32 v124, v0
	v_mov_b32_e32 v125, v0
	v_mov_b32_e32 v126, v0
	v_mov_b32_e32 v127, v0
	.p2align 6

; template <class Epi, bool ALIGN_EPI = PG8_ALIGN>
; __device__ __forceinline__ void gemm_phase(LAS unsigned char* lds, const Gemm g, const StaticOrder S, const Epi E) {
;     ...
;         const bool has_next = S.next(ui + 1, nxt);
;         const char* nA = has_next ? (const char*)g.A + (size_t)nxt.pm * tstepA : cA; const char* nB = has_next ? (const char*)g.Bt + (size_t)nxt.pn * tstepB : cB;
;         for (int t = 0; t < nt; t += 2) {
;             const bool last = (t == nt - 2);
;             const char* a1 = cA + (size_t)(t + 1) * kstep;
;             const char* a2 = last ? nA : cA + (size_t)(t + 2) * kstep; const char* b2 = last ? nB : cB + (size_t)(t + 2) * kstep;
;             const char* a3 = a2 + kstep; const char* b3 = b2 + kstep;
;     ...
; #pragma unroll
;         for (int a = 0; a < 2; ++a)
; #pragma unroll
;             for (int b = 0; b < 2; ++b)
; #pragma unroll
;                 for (int m = 0; m < 4; ++m)
; #pragma unroll
;                     for (int n = 0; n < 2; ++n) acc[a][b][m][n] = (f32x4){0.f, 0.f, 0.f, 0.f};
;         cur = nxt; cA = nA; cB = nB; ++ui;
.LBB0_868:
	s_ashr_i32 s29, s28, 31
	s_lshl_b64 s[0:1], s[28:29], 18
	s_add_u32 s36, s16, s0
	s_addc_u32 s37, s17, s1
	s_and_b64 s[0:1], s[2:3], exec
	s_cselect_b32 s29, s37, s51
	s_cselect_b32 s66, s36, s50
	s_ashr_i32 s27, s26, 31
	s_lshl_b64 s[0:1], s[26:27], 18
	s_add_u32 s44, s38, s0
	s_addc_u32 s45, s83, s1
	s_and_b64 s[0:1], s[2:3], exec
	s_cselect_b32 s27, s45, s53
	s_cselect_b32 s67, s44, s52
	s_add_u32 s50, s50, 0x20080
	s_addc_u32 s51, s51, 0
	s_add_u32 s68, s52, 0x100
	v_mov_b32_e32 v0, 0
	s_addc_u32 s69, s53, 0
	s_mov_b32 s71, -2
	v_mov_b32_e32 v1, v0
	v_mov_b32_e32 v2, v0
	v_mov_b32_e32 v3, v0
	v_mov_b32_e32 v4, v0
	v_mov_b32_e32 v5, v0
	v_mov_b32_e32 v6, v0
	v_mov_b32_e32 v7, v0
	v_mov_b32_e32 v8, v0
	v_mov_b32_e32 v9, v0
	v_mov_b32_e32 v10, v0
	v_mov_b32_e32 v11, v0
	v_mov_b32_e32 v12, v0
	v_mov_b32_e32 v13, v0
	v_mov_b32_e32 v14, v0
	v_mov_b32_e32 v15, v0
	v_mov_b32_e32 v16, v0
	v_mov_b32_e32 v17, v0
	v_mov_b32_e32 v18, v0
	v_mov_b32_e32 v19, v0
	v_mov_b32_e32 v20, v0
	v_mov_b32_e32 v21, v0
	v_mov_b32_e32 v22, v0
	v_mov_b32_e32 v23, v0
	v_mov_b32_e32 v24, v0
	v_mov_b32_e32 v25, v0
	v_mov_b32_e32 v26, v0
	v_mov_b32_e32 v27, v0
	v_mov_b32_e32 v28, v0
	v_mov_b32_e32 v29, v0
	v_mov_b32_e32 v30, v0
	v_mov_b32_e32 v31, v0
	v_mov_b32_e32 v36, v0
	v_mov_b32_e32 v37, v0
	v_mov_b32_e32 v38, v0
	v_mov_b32_e32 v39, v0
	v_mov_b32_e32 v44, v0
	v_mov_b32_e32 v45, v0
	v_mov_b32_e32 v46, v0
	v_mov_b32_e32 v47, v0
	v_mov_b32_e32 v56, v0
	v_mov_b32_e32 v57, v0
	v_mov_b32_e32 v58, v0
	v_mov_b32_e32 v59, v0
	v_mov_b32_e32 v60, v0
	v_mov_b32_e32 v61, v0
	v_mov_b32_e32 v62, v0
	v_mov_b32_e32 v63, v0
	v_mov_b32_e32 v72, v0
	v_mov_b32_e32 v73, v0
	v_mov_b32_e32 v74, v0
	v_mov_b32_e32 v75, v0
	v_mov_b32_e32 v80, v0
	v_mov_b32_e32 v81, v0
	v_mov_b32_e32 v82, v0
	v_mov_b32_e32 v83, v0
	v_mov_b32_e32 v88, v0
	v_mov_b32_e32 v89, v0
	v_mov_b32_e32 v90, v0
	v_mov_b32_e32 v91, v0
	v_mov_b32_e32 v92, v0
	v_mov_b32_e32 v93, v0
	v_mov_b32_e32 v94, v0
	v_mov_b32_e32 v95, v0
	v_mov_b32_e32 v32, v0
	v_mov_b32_e32 v33, v0
	v_mov_b32_e32 v34, v0
	v_mov_b32_e32 v35, v0
	v_mov_b32_e32 v40, v0
	v_mov_b32_e32 v41, v0
	v_mov_b32_e32 v42, v0
	v_mov_b32_e32 v43, v0
	v_mov_b32_e32 v48, v0
	v_mov_b32_e32 v49, v0
	v_mov_b32_e32 v50, v0
	v_mov_b32_e32 v51, v0
	v_mov_b32_e32 v52, v0
	v_mov_b32_e32 v53, v0
	v_mov_b32_e32 v54, v0
	v_mov_b32_e32 v55, v0
	v_mov_b32_e32 v64, v0
	v_mov_b32_e32 v65, v0
	v_mov_b32_e32 v66, v0
	v_mov_b32_e32 v67, v0
	v_mov_b32_e32 v68, v0
	v_mov_b32_e32 v69, v0
	v_mov_b32_e32 v70, v0
	v_mov_b32_e32 v71, v0
	v_mov_b32_e32 v76, v0
	v_mov_b32_e32 v77, v0
	v_mov_b32_e32 v78, v0
	v_mov_b32_e32 v79, v0
	v_mov_b32_e32 v84, v0
	v_mov_b32_e32 v85, v0
	v_mov_b32_e32 v86, v0
	v_mov_b32_e32 v87, v0
	v_mov_b32_e32 v96, v0
	v_mov_b32_e32 v97, v0
	v_mov_b32_e32 v98, v0
	v_mov_b32_e32 v99, v0
	v_mov_b32_e32 v100, v0
	v_mov_b32_e32 v101, v0
	v_mov_b32_e32 v102, v0
	v_mov_b32_e32 v103, v0
	v_mov_b32_e32 v104, v0
	v_mov_b32_e32 v105, v0
	v_mov_b32_e32 v106, v0
	v_mov_b32_e32 v107, v0
	v_mov_b32_e32 v108, v0
	v_mov_b32_e32 v109, v0
	v_mov_b32_e32 v110, v0
	v_mov_b32_e32 v111, v0
	v_mov_b32_e32 v112, v0
	v_mov_b32_e32 v113, v0
	v_mov_b32_e32 v114, v0
	v_mov_b32_e32 v115, v0
	v_mov_b32_e32 v116, v0
	v_mov_b32_e32 v117, v0
	v_mov_b32_e32 v118, v0
	v_mov_b32_e32 v119, v0
	v_mov_b32_e32 v120, v0
	v_mov_b32_e32 v121, v0
	v_mov_b32_e32 v122, v0
	v_mov_b32_e32 v123, v0
	v_mov_b32_e32 v124, v0
	v_mov_b32_e32 v125, v0
	v_mov_b32_e32 v126, v0
	v_mov_b32_e32 v127, v0
	.p2align 6

; template <class Epi, bool ALIGN_EPI = PG8_ALIGN>
; __device__ __forceinline__ void gemm_phase(LAS unsigned char* lds, const Gemm g, const StaticOrder S, const Epi E) {
;     ...
;         const bool has_next = S.next(ui + 1, nxt);
;         const char* nA = has_next ? (const char*)g.A + (size_t)nxt.pm * tstepA : cA; const char* nB = has_next ? (const char*)g.Bt + (size_t)nxt.pn * tstepB : cB;
;         for (int t = 0; t < nt; t += 2) {
;             const bool last = (t == nt - 2);
;             const char* a1 = cA + (size_t)(t + 1) * kstep;
;             const char* a2 = last ? nA : cA + (size_t)(t + 2) * kstep; const char* b2 = last ? nB : cB + (size_t)(t + 2) * kstep;
;             const char* a3 = a2 + kstep; const char* b3 = b2 + kstep;
;     ...
; #pragma unroll
;         for (int a = 0; a < 2; ++a)
; #pragma unroll
;             for (int b = 0; b < 2; ++b)
; #pragma unroll
;                 for (int m = 0; m < 4; ++m)
; #pragma unroll
;                     for (int n = 0; n < 2; ++n) acc[a][b][m][n] = (f32x4){0.f, 0.f, 0.f, 0.f};
;         cur = nxt; cA = nA; cB = nB; ++ui;
.LBB0_892:
	s_ashr_i32 s29, s28, 31
	s_lshl_b64 s[0:1], s[28:29], 17
	s_add_u32 s50, s71, s0
	s_addc_u32 s51, s72, s1
	s_and_b64 s[0:1], s[2:3], exec
	s_cselect_b32 s29, s51, s45
	s_cselect_b32 s83, s50, s44
	s_ashr_i32 s27, s26, 31
	s_lshl_b64 s[0:1], s[26:27], 17
	v_readlane_b32 s27, v238, 49
	s_add_u32 s52, s27, s0
	v_readlane_b32 s0, v238, 50
	s_addc_u32 s53, s0, s1
	s_and_b64 s[0:1], s[2:3], exec
	v_mov_b32_e32 v0, 0
	s_cselect_b32 s27, s53, s37
	s_cselect_b32 s90, s52, s36
	s_mov_b32 s60, 0
	s_mov_b64 s[54:55], -1
	s_mov_b64 s[58:59], 0
	v_mov_b32_e32 v1, v0
	v_mov_b32_e32 v2, v0
	v_mov_b32_e32 v3, v0
	v_mov_b32_e32 v4, v0
	v_mov_b32_e32 v5, v0
	v_mov_b32_e32 v6, v0
	v_mov_b32_e32 v7, v0
	v_mov_b32_e32 v8, v0
	v_mov_b32_e32 v9, v0
	v_mov_b32_e32 v10, v0
	v_mov_b32_e32 v11, v0
	v_mov_b32_e32 v12, v0
	v_mov_b32_e32 v13, v0
	v_mov_b32_e32 v14, v0
	v_mov_b32_e32 v15, v0
	v_mov_b32_e32 v16, v0
	v_mov_b32_e32 v17, v0
	v_mov_b32_e32 v18, v0
	v_mov_b32_e32 v19, v0
	v_mov_b32_e32 v20, v0
	v_mov_b32_e32 v21, v0
	v_mov_b32_e32 v22, v0
	v_mov_b32_e32 v23, v0
	v_mov_b32_e32 v24, v0
	v_mov_b32_e32 v25, v0
	v_mov_b32_e32 v26, v0
	v_mov_b32_e32 v27, v0
	v_mov_b32_e32 v28, v0
	v_mov_b32_e32 v29, v0
	v_mov_b32_e32 v30, v0
	v_mov_b32_e32 v31, v0
	v_mov_b32_e32 v40, v0
	v_mov_b32_e32 v41, v0
	v_mov_b32_e32 v42, v0
	v_mov_b32_e32 v43, v0
	v_mov_b32_e32 v48, v0
	v_mov_b32_e32 v49, v0
	v_mov_b32_e32 v50, v0
	v_mov_b32_e32 v51, v0
	v_mov_b32_e32 v56, v0
	v_mov_b32_e32 v57, v0
	v_mov_b32_e32 v58, v0
	v_mov_b32_e32 v59, v0
	v_mov_b32_e32 v64, v0
	v_mov_b32_e32 v65, v0
	v_mov_b32_e32 v66, v0
	v_mov_b32_e32 v67, v0
	v_mov_b32_e32 v72, v0
	v_mov_b32_e32 v73, v0
	v_mov_b32_e32 v74, v0
	v_mov_b32_e32 v75, v0
	v_mov_b32_e32 v80, v0
	v_mov_b32_e32 v81, v0
	v_mov_b32_e32 v82, v0
	v_mov_b32_e32 v83, v0
	v_mov_b32_e32 v88, v0
	v_mov_b32_e32 v89, v0
	v_mov_b32_e32 v90, v0
	v_mov_b32_e32 v91, v0
	v_mov_b32_e32 v92, v0
	v_mov_b32_e32 v93, v0
	v_mov_b32_e32 v94, v0
	v_mov_b32_e32 v95, v0
	v_mov_b32_e32 v32, v0
	v_mov_b32_e32 v33, v0
	v_mov_b32_e32 v34, v0
	v_mov_b32_e32 v35, v0
	v_mov_b32_e32 v36, v0
	v_mov_b32_e32 v37, v0
	v_mov_b32_e32 v38, v0
	v_mov_b32_e32 v39, v0
	v_mov_b32_e32 v44, v0
	v_mov_b32_e32 v45, v0
	v_mov_b32_e32 v46, v0
	v_mov_b32_e32 v47, v0
	v_mov_b32_e32 v52, v0
	v_mov_b32_e32 v53, v0
	v_mov_b32_e32 v54, v0
	v_mov_b32_e32 v55, v0
	v_mov_b32_e32 v60, v0
	v_mov_b32_e32 v61, v0
	v_mov_b32_e32 v62, v0
	v_mov_b32_e32 v63, v0
	v_mov_b32_e32 v68, v0
	v_mov_b32_e32 v69, v0
	v_mov_b32_e32 v70, v0
	v_mov_b32_e32 v71, v0
	v_mov_b32_e32 v76, v0
	v_mov_b32_e32 v77, v0
	v_mov_b32_e32 v78, v0
	v_mov_b32_e32 v79, v0
	v_mov_b32_e32 v84, v0
	v_mov_b32_e32 v85, v0
	v_mov_b32_e32 v86, v0
	v_mov_b32_e32 v87, v0
	v_mov_b32_e32 v96, v0
	v_mov_b32_e32 v97, v0
	v_mov_b32_e32 v98, v0
	v_mov_b32_e32 v99, v0
	v_mov_b32_e32 v100, v0
	v_mov_b32_e32 v101, v0
	v_mov_b32_e32 v102, v0
	v_mov_b32_e32 v103, v0
	v_mov_b32_e32 v104, v0
	v_mov_b32_e32 v105, v0
	v_mov_b32_e32 v106, v0
	v_mov_b32_e32 v107, v0
	v_mov_b32_e32 v108, v0
	v_mov_b32_e32 v109, v0
	v_mov_b32_e32 v110, v0
	v_mov_b32_e32 v111, v0
	v_mov_b32_e32 v112, v0
	v_mov_b32_e32 v113, v0
	v_mov_b32_e32 v114, v0
	v_mov_b32_e32 v115, v0
	v_mov_b32_e32 v116, v0
	v_mov_b32_e32 v117, v0
	v_mov_b32_e32 v118, v0
	v_mov_b32_e32 v119, v0
	v_mov_b32_e32 v120, v0
	v_mov_b32_e32 v121, v0
	v_mov_b32_e32 v122, v0
	v_mov_b32_e32 v123, v0
	v_mov_b32_e32 v124, v0
	v_mov_b32_e32 v125, v0
	v_mov_b32_e32 v126, v0
	v_mov_b32_e32 v127, v0
	.p2align 6

; template <class Epi, bool ALIGN_EPI = PG8_ALIGN>
; __device__ __forceinline__ void gemm_phase(LAS unsigned char* lds, const Gemm g, const StaticOrder S, const Epi E) {
;     ...
;         const bool has_next = S.next(ui + 1, nxt);
;         const char* nA = has_next ? (const char*)g.A + (size_t)nxt.pm * tstepA : cA; const char* nB = has_next ? (const char*)g.Bt + (size_t)nxt.pn * tstepB : cB;
;         for (int t = 0; t < nt; t += 2) {
;             const bool last = (t == nt - 2);
;             const char* a1 = cA + (size_t)(t + 1) * kstep;
;             const char* a2 = last ? nA : cA + (size_t)(t + 2) * kstep; const char* b2 = last ? nB : cB + (size_t)(t + 2) * kstep;
;             const char* a3 = a2 + kstep; const char* b3 = b2 + kstep;
;     ...
; #pragma unroll
;         for (int a = 0; a < 2; ++a)
; #pragma unroll
;             for (int b = 0; b < 2; ++b)
; #pragma unroll
;                 for (int m = 0; m < 4; ++m)
; #pragma unroll
;                     for (int n = 0; n < 2; ++n) acc[a][b][m][n] = (f32x4){0.f, 0.f, 0.f, 0.f};
;         cur = nxt; cA = nA; cB = nB; ++ui;
.LBB0_916:
	s_ashr_i32 s27, s26, 31
	s_lshl_b64 s[0:1], s[26:27], 17
	s_add_u32 s44, s14, s0
	s_addc_u32 s45, s16, s1
	s_and_b64 s[0:1], s[2:3], exec
	s_cselect_b32 s27, s45, s51
	s_cselect_b32 s81, s44, s50
	s_ashr_i32 s25, s24, 31
	s_lshl_b64 s[0:1], s[24:25], 17
	s_add_u32 s52, s71, s0
	s_addc_u32 s53, s72, s1
	s_and_b64 s[0:1], s[2:3], exec
	v_mov_b32_e32 v0, 0
	s_cselect_b32 s25, s53, s37
	s_cselect_b32 s82, s52, s36
	s_mov_b32 s60, 0
	s_mov_b64 s[54:55], -1
	s_mov_b64 s[58:59], 0
	v_mov_b32_e32 v1, v0
	v_mov_b32_e32 v2, v0
	v_mov_b32_e32 v3, v0
	v_mov_b32_e32 v4, v0
	v_mov_b32_e32 v5, v0
	v_mov_b32_e32 v6, v0
	v_mov_b32_e32 v7, v0
	v_mov_b32_e32 v8, v0
	v_mov_b32_e32 v9, v0
	v_mov_b32_e32 v10, v0
	v_mov_b32_e32 v11, v0
	v_mov_b32_e32 v12, v0
	v_mov_b32_e32 v13, v0
	v_mov_b32_e32 v14, v0
	v_mov_b32_e32 v15, v0
	v_mov_b32_e32 v16, v0
	v_mov_b32_e32 v17, v0
	v_mov_b32_e32 v18, v0
	v_mov_b32_e32 v19, v0
	v_mov_b32_e32 v20, v0
	v_mov_b32_e32 v21, v0
	v_mov_b32_e32 v22, v0
	v_mov_b32_e32 v23, v0
	v_mov_b32_e32 v24, v0
	v_mov_b32_e32 v25, v0
	v_mov_b32_e32 v26, v0
	v_mov_b32_e32 v27, v0
	v_mov_b32_e32 v28, v0
	v_mov_b32_e32 v29, v0
	v_mov_b32_e32 v30, v0
	v_mov_b32_e32 v31, v0
	v_mov_b32_e32 v40, v0
	v_mov_b32_e32 v41, v0
	v_mov_b32_e32 v42, v0
	v_mov_b32_e32 v43, v0
	v_mov_b32_e32 v44, v0
	v_mov_b32_e32 v45, v0
	v_mov_b32_e32 v46, v0
	v_mov_b32_e32 v47, v0
	v_mov_b32_e32 v60, v0
	v_mov_b32_e32 v61, v0
	v_mov_b32_e32 v62, v0
	v_mov_b32_e32 v63, v0
	v_mov_b32_e32 v68, v0
	v_mov_b32_e32 v69, v0
	v_mov_b32_e32 v70, v0
	v_mov_b32_e32 v71, v0
	v_mov_b32_e32 v80, v0
	v_mov_b32_e32 v81, v0
	v_mov_b32_e32 v82, v0
	v_mov_b32_e32 v83, v0
	v_mov_b32_e32 v84, v0
	v_mov_b32_e32 v85, v0
	v_mov_b32_e32 v86, v0
	v_mov_b32_e32 v87, v0
	v_mov_b32_e32 v88, v0
	v_mov_b32_e32 v89, v0
	v_mov_b32_e32 v90, v0
	v_mov_b32_e32 v91, v0
	v_mov_b32_e32 v92, v0
	v_mov_b32_e32 v93, v0
	v_mov_b32_e32 v94, v0
	v_mov_b32_e32 v95, v0
	v_mov_b32_e32 v32, v0
	v_mov_b32_e32 v33, v0
	v_mov_b32_e32 v34, v0
	v_mov_b32_e32 v35, v0
	v_mov_b32_e32 v36, v0
	v_mov_b32_e32 v37, v0
	v_mov_b32_e32 v38, v0
	v_mov_b32_e32 v39, v0
	v_mov_b32_e32 v48, v0
	v_mov_b32_e32 v49, v0
	v_mov_b32_e32 v50, v0
	v_mov_b32_e32 v51, v0
	v_mov_b32_e32 v52, v0
	v_mov_b32_e32 v53, v0
	v_mov_b32_e32 v54, v0
	v_mov_b32_e32 v55, v0
	v_mov_b32_e32 v56, v0
	v_mov_b32_e32 v57, v0
	v_mov_b32_e32 v58, v0
	v_mov_b32_e32 v59, v0
	v_mov_b32_e32 v64, v0
	v_mov_b32_e32 v65, v0
	v_mov_b32_e32 v66, v0
	v_mov_b32_e32 v67, v0
	v_mov_b32_e32 v72, v0
	v_mov_b32_e32 v73, v0
	v_mov_b32_e32 v74, v0
	v_mov_b32_e32 v75, v0
	v_mov_b32_e32 v76, v0
	v_mov_b32_e32 v77, v0
	v_mov_b32_e32 v78, v0
	v_mov_b32_e32 v79, v0
	v_mov_b32_e32 v96, v0
	v_mov_b32_e32 v97, v0
	v_mov_b32_e32 v98, v0
	v_mov_b32_e32 v99, v0
	v_mov_b32_e32 v100, v0
	v_mov_b32_e32 v101, v0
	v_mov_b32_e32 v102, v0
	v_mov_b32_e32 v103, v0
	v_mov_b32_e32 v104, v0
	v_mov_b32_e32 v105, v0
	v_mov_b32_e32 v106, v0
	v_mov_b32_e32 v107, v0
	v_mov_b32_e32 v108, v0
	v_mov_b32_e32 v109, v0
	v_mov_b32_e32 v110, v0
	v_mov_b32_e32 v111, v0
	v_mov_b32_e32 v112, v0
	v_mov_b32_e32 v113, v0
	v_mov_b32_e32 v114, v0
	v_mov_b32_e32 v115, v0
	v_mov_b32_e32 v116, v0
	v_mov_b32_e32 v117, v0
	v_mov_b32_e32 v118, v0
	v_mov_b32_e32 v119, v0
	v_mov_b32_e32 v120, v0
	v_mov_b32_e32 v121, v0
	v_mov_b32_e32 v122, v0
	v_mov_b32_e32 v123, v0
	v_mov_b32_e32 v124, v0
	v_mov_b32_e32 v125, v0
	v_mov_b32_e32 v126, v0
	v_mov_b32_e32 v127, v0
	.p2align 6

; template <class Epi, bool ALIGN_EPI = PG8_ALIGN>
; __device__ __forceinline__ void gemm_phase(LAS unsigned char* lds, const Gemm g, const StaticOrder S, const Epi E) {
;     ...
;         const bool has_next = S.next(ui + 1, nxt);
;         const char* nA = has_next ? (const char*)g.A + (size_t)nxt.pm * tstepA : cA; const char* nB = has_next ? (const char*)g.Bt + (size_t)nxt.pn * tstepB : cB;
;         for (int t = 0; t < nt; t += 2) {
;             const bool last = (t == nt - 2);
;             const char* a1 = cA + (size_t)(t + 1) * kstep;
;             const char* a2 = last ? nA : cA + (size_t)(t + 2) * kstep; const char* b2 = last ? nB : cB + (size_t)(t + 2) * kstep;
;             const char* a3 = a2 + kstep; const char* b3 = b2 + kstep;
;     ...
; #pragma unroll
;         for (int a = 0; a < 2; ++a)
; #pragma unroll
;             for (int b = 0; b < 2; ++b)
; #pragma unroll
;                 for (int m = 0; m < 4; ++m)
; #pragma unroll
;                     for (int n = 0; n < 2; ++n) acc[a][b][m][n] = (f32x4){0.f, 0.f, 0.f, 0.f};
;         cur = nxt; cA = nA; cB = nB; ++ui;
.LBB0_1204:
	s_ashr_i32 s37, s36, 31
	s_lshl_b64 s[16:17], s[36:37], 20
	s_add_u32 s38, s40, s16
	s_addc_u32 s39, s41, s17
	s_and_b64 s[16:17], s[4:5], exec
	s_cselect_b32 s13, s39, s47
	s_cselect_b32 s14, s38, s46
	s_ashr_i32 s29, s28, 31
	s_lshl_b64 s[16:17], s[28:29], 20
	v_readlane_b32 s29, v238, 40
	s_add_u32 s42, s29, s16
	v_readlane_b32 s16, v238, 41
	s_addc_u32 s43, s16, s17
	s_and_b64 s[16:17], s[4:5], exec
	s_cselect_b32 s16, s43, s49
	s_cselect_b32 s17, s42, s48
	s_add_u32 s46, s46, 0x80080
	s_addc_u32 s47, s47, 0
	s_add_u32 s29, s48, 0x100
	v_mov_b32_e32 v0, 0
	s_addc_u32 s33, s49, 0
	s_mov_b32 s34, -2
	v_mov_b32_e32 v1, v0
	v_mov_b32_e32 v2, v0
	v_mov_b32_e32 v3, v0
	v_mov_b32_e32 v4, v0
	v_mov_b32_e32 v5, v0
	v_mov_b32_e32 v6, v0
	v_mov_b32_e32 v7, v0
	v_mov_b32_e32 v16, v0
	v_mov_b32_e32 v17, v0
	v_mov_b32_e32 v18, v0
	v_mov_b32_e32 v19, v0
	v_mov_b32_e32 v20, v0
	v_mov_b32_e32 v21, v0
	v_mov_b32_e32 v22, v0
	v_mov_b32_e32 v23, v0
	v_mov_b32_e32 v32, v0
	v_mov_b32_e32 v33, v0
	v_mov_b32_e32 v34, v0
	v_mov_b32_e32 v35, v0
	v_mov_b32_e32 v36, v0
	v_mov_b32_e32 v37, v0
	v_mov_b32_e32 v38, v0
	v_mov_b32_e32 v39, v0
	v_mov_b32_e32 v48, v0
	v_mov_b32_e32 v49, v0
	v_mov_b32_e32 v50, v0
	v_mov_b32_e32 v51, v0
	v_mov_b32_e32 v52, v0
	v_mov_b32_e32 v53, v0
	v_mov_b32_e32 v54, v0
	v_mov_b32_e32 v55, v0
	v_mov_b32_e32 v8, v0
	v_mov_b32_e32 v9, v0
	v_mov_b32_e32 v10, v0
	v_mov_b32_e32 v11, v0
	v_mov_b32_e32 v12, v0
	v_mov_b32_e32 v13, v0
	v_mov_b32_e32 v14, v0
	v_mov_b32_e32 v15, v0
	v_mov_b32_e32 v24, v0
	v_mov_b32_e32 v25, v0
	v_mov_b32_e32 v26, v0
	v_mov_b32_e32 v27, v0
	v_mov_b32_e32 v28, v0
	v_mov_b32_e32 v29, v0
	v_mov_b32_e32 v30, v0
	v_mov_b32_e32 v31, v0
	v_mov_b32_e32 v40, v0
	v_mov_b32_e32 v41, v0
	v_mov_b32_e32 v42, v0
	v_mov_b32_e32 v43, v0
	v_mov_b32_e32 v44, v0
	v_mov_b32_e32 v45, v0
	v_mov_b32_e32 v46, v0
	v_mov_b32_e32 v47, v0
	v_mov_b32_e32 v56, v0
	v_mov_b32_e32 v57, v0
	v_mov_b32_e32 v58, v0
	v_mov_b32_e32 v59, v0
	v_mov_b32_e32 v60, v0
	v_mov_b32_e32 v61, v0
	v_mov_b32_e32 v62, v0
	v_mov_b32_e32 v63, v0
	v_mov_b32_e32 v64, v0
	v_mov_b32_e32 v65, v0
	v_mov_b32_e32 v66, v0
	v_mov_b32_e32 v67, v0
	v_mov_b32_e32 v68, v0
	v_mov_b32_e32 v69, v0
	v_mov_b32_e32 v70, v0
	v_mov_b32_e32 v71, v0
	v_mov_b32_e32 v80, v0
	v_mov_b32_e32 v81, v0
	v_mov_b32_e32 v82, v0
	v_mov_b32_e32 v83, v0
	v_mov_b32_e32 v84, v0
	v_mov_b32_e32 v85, v0
	v_mov_b32_e32 v86, v0
	v_mov_b32_e32 v87, v0
	v_mov_b32_e32 v96, v0
	v_mov_b32_e32 v97, v0
	v_mov_b32_e32 v98, v0
	v_mov_b32_e32 v99, v0
	v_mov_b32_e32 v100, v0
	v_mov_b32_e32 v101, v0
	v_mov_b32_e32 v102, v0
	v_mov_b32_e32 v103, v0
	v_mov_b32_e32 v112, v0
	v_mov_b32_e32 v113, v0
	v_mov_b32_e32 v114, v0
	v_mov_b32_e32 v115, v0
	v_mov_b32_e32 v116, v0
	v_mov_b32_e32 v117, v0
	v_mov_b32_e32 v118, v0
	v_mov_b32_e32 v119, v0
	v_mov_b32_e32 v72, v0
	v_mov_b32_e32 v73, v0
	v_mov_b32_e32 v74, v0
	v_mov_b32_e32 v75, v0
	v_mov_b32_e32 v76, v0
	v_mov_b32_e32 v77, v0
	v_mov_b32_e32 v78, v0
	v_mov_b32_e32 v79, v0
	v_mov_b32_e32 v88, v0
	v_mov_b32_e32 v89, v0
	v_mov_b32_e32 v90, v0
	v_mov_b32_e32 v91, v0
	v_mov_b32_e32 v92, v0
	v_mov_b32_e32 v93, v0
	v_mov_b32_e32 v94, v0
	v_mov_b32_e32 v95, v0
	v_mov_b32_e32 v104, v0
	v_mov_b32_e32 v105, v0
	v_mov_b32_e32 v106, v0
	v_mov_b32_e32 v107, v0
	v_mov_b32_e32 v108, v0
	v_mov_b32_e32 v109, v0
	v_mov_b32_e32 v110, v0
	v_mov_b32_e32 v111, v0
	v_mov_b32_e32 v120, v0
	v_mov_b32_e32 v121, v0
	v_mov_b32_e32 v122, v0
	v_mov_b32_e32 v123, v0
	v_mov_b32_e32 v124, v0
	v_mov_b32_e32 v125, v0
	v_mov_b32_e32 v126, v0
	v_mov_b32_e32 v127, v0
	.p2align 6

; template <class Epi, bool ALIGN_EPI = PG8_ALIGN>
; __device__ __forceinline__ void gemm_phase(LAS unsigned char* lds, const Gemm g, const StaticOrder S, const Epi E) {
;     ...
;         const bool has_next = S.next(ui + 1, nxt);
;         const char* nA = has_next ? (const char*)g.A + (size_t)nxt.pm * tstepA : cA; const char* nB = has_next ? (const char*)g.Bt + (size_t)nxt.pn * tstepB : cB;
;         for (int t = 0; t < nt; t += 2) {
;             const bool last = (t == nt - 2);
;             const char* a1 = cA + (size_t)(t + 1) * kstep;
;             const char* a2 = last ? nA : cA + (size_t)(t + 2) * kstep; const char* b2 = last ? nB : cB + (size_t)(t + 2) * kstep;
;             const char* a3 = a2 + kstep; const char* b3 = b2 + kstep;
;     ...
; #pragma unroll
;         for (int a = 0; a < 2; ++a)
; #pragma unroll
;             for (int b = 0; b < 2; ++b)
; #pragma unroll
;                 for (int m = 0; m < 4; ++m)
; #pragma unroll
;                     for (int n = 0; n < 2; ++n) acc[a][b][m][n] = (f32x4){0.f, 0.f, 0.f, 0.f};
;         cur = nxt; cA = nA; cB = nB; ++ui;
.LBB0_1299:
	s_ashr_i32 s47, s46, 31
	s_lshl_b64 s[48:49], s[46:47], 20
	s_add_u32 s48, s6, s48
	s_addc_u32 s49, s7, s49
	s_and_b64 s[50:51], s[2:3], exec
	s_cselect_b32 s47, s49, s53
	s_cselect_b32 s69, s48, s52
	s_ashr_i32 s45, s44, 31
	s_lshl_b64 s[50:51], s[44:45], 20
	v_readlane_b32 s45, v238, 44
	s_add_u32 s50, s45, s50
	v_readlane_b32 s45, v238, 45
	s_addc_u32 s51, s45, s51
	s_and_b64 s[56:57], s[2:3], exec
	s_cselect_b32 s45, s51, s55
	s_cselect_b32 s70, s50, s54
	s_add_u32 s52, s52, 0x80080
	s_addc_u32 s53, s53, 0
	s_add_u32 s71, s54, 0x100
	v_mov_b32_e32 v0, 0
	s_addc_u32 s72, s55, 0
	s_mov_b32 s73, -2
	v_mov_b32_e32 v1, v0
	v_mov_b32_e32 v2, v0
	v_mov_b32_e32 v3, v0
	v_mov_b32_e32 v4, v0
	v_mov_b32_e32 v5, v0
	v_mov_b32_e32 v6, v0
	v_mov_b32_e32 v7, v0
	v_mov_b32_e32 v8, v0
	v_mov_b32_e32 v9, v0
	v_mov_b32_e32 v10, v0
	v_mov_b32_e32 v11, v0
	v_mov_b32_e32 v12, v0
	v_mov_b32_e32 v13, v0
	v_mov_b32_e32 v14, v0
	v_mov_b32_e32 v15, v0
	v_mov_b32_e32 v16, v0
	v_mov_b32_e32 v17, v0
	v_mov_b32_e32 v18, v0
	v_mov_b32_e32 v19, v0
	v_mov_b32_e32 v20, v0
	v_mov_b32_e32 v21, v0
	v_mov_b32_e32 v22, v0
	v_mov_b32_e32 v23, v0
	v_mov_b32_e32 v24, v0
	v_mov_b32_e32 v25, v0
	v_mov_b32_e32 v26, v0
	v_mov_b32_e32 v27, v0
	v_mov_b32_e32 v28, v0
	v_mov_b32_e32 v29, v0
	v_mov_b32_e32 v30, v0
	v_mov_b32_e32 v31, v0
	v_mov_b32_e32 v52, v0
	v_mov_b32_e32 v53, v0
	v_mov_b32_e32 v54, v0
	v_mov_b32_e32 v55, v0
	v_mov_b32_e32 v60, v0
	v_mov_b32_e32 v61, v0
	v_mov_b32_e32 v62, v0
	v_mov_b32_e32 v63, v0
	v_mov_b32_e32 v72, v0
	v_mov_b32_e32 v73, v0
	v_mov_b32_e32 v74, v0
	v_mov_b32_e32 v75, v0
	v_mov_b32_e32 v76, v0
	v_mov_b32_e32 v77, v0
	v_mov_b32_e32 v78, v0
	v_mov_b32_e32 v79, v0
	v_mov_b32_e32 v80, v0
	v_mov_b32_e32 v81, v0
	v_mov_b32_e32 v82, v0
	v_mov_b32_e32 v83, v0
	v_mov_b32_e32 v84, v0
	v_mov_b32_e32 v85, v0
	v_mov_b32_e32 v86, v0
	v_mov_b32_e32 v87, v0
	v_mov_b32_e32 v88, v0
	v_mov_b32_e32 v89, v0
	v_mov_b32_e32 v90, v0
	v_mov_b32_e32 v91, v0
	v_mov_b32_e32 v92, v0
	v_mov_b32_e32 v93, v0
	v_mov_b32_e32 v94, v0
	v_mov_b32_e32 v95, v0
	v_mov_b32_e32 v32, v0
	v_mov_b32_e32 v33, v0
	v_mov_b32_e32 v34, v0
	v_mov_b32_e32 v35, v0
	v_mov_b32_e32 v36, v0
	v_mov_b32_e32 v37, v0
	v_mov_b32_e32 v38, v0
	v_mov_b32_e32 v39, v0
	v_mov_b32_e32 v40, v0
	v_mov_b32_e32 v41, v0
	v_mov_b32_e32 v42, v0
	v_mov_b32_e32 v43, v0
	v_mov_b32_e32 v44, v0
	v_mov_b32_e32 v45, v0
	v_mov_b32_e32 v46, v0
	v_mov_b32_e32 v47, v0
	v_mov_b32_e32 v48, v0
	v_mov_b32_e32 v49, v0
	v_mov_b32_e32 v50, v0
	v_mov_b32_e32 v51, v0
	v_mov_b32_e32 v56, v0
	v_mov_b32_e32 v57, v0
	v_mov_b32_e32 v58, v0
	v_mov_b32_e32 v59, v0
	v_mov_b32_e32 v64, v0
	v_mov_b32_e32 v65, v0
	v_mov_b32_e32 v66, v0
	v_mov_b32_e32 v67, v0
	v_mov_b32_e32 v68, v0
	v_mov_b32_e32 v69, v0
	v_mov_b32_e32 v70, v0
	v_mov_b32_e32 v71, v0
	v_mov_b32_e32 v96, v0
	v_mov_b32_e32 v97, v0
	v_mov_b32_e32 v98, v0
	v_mov_b32_e32 v99, v0
	v_mov_b32_e32 v100, v0
	v_mov_b32_e32 v101, v0
	v_mov_b32_e32 v102, v0
	v_mov_b32_e32 v103, v0
	v_mov_b32_e32 v104, v0
	v_mov_b32_e32 v105, v0
	v_mov_b32_e32 v106, v0
	v_mov_b32_e32 v107, v0
	v_mov_b32_e32 v108, v0
	v_mov_b32_e32 v109, v0
	v_mov_b32_e32 v110, v0
	v_mov_b32_e32 v111, v0
	v_mov_b32_e32 v112, v0
	v_mov_b32_e32 v113, v0
	v_mov_b32_e32 v114, v0
	v_mov_b32_e32 v115, v0
	v_mov_b32_e32 v116, v0
	v_mov_b32_e32 v117, v0
	v_mov_b32_e32 v118, v0
	v_mov_b32_e32 v119, v0
	v_mov_b32_e32 v120, v0
	v_mov_b32_e32 v121, v0
	v_mov_b32_e32 v122, v0
	v_mov_b32_e32 v123, v0
	v_mov_b32_e32 v124, v0
	v_mov_b32_e32 v125, v0
	v_mov_b32_e32 v126, v0
	v_mov_b32_e32 v127, v0
	.p2align 6

; template <class Epi, bool ALIGN_EPI = PG8_ALIGN>
; __device__ __forceinline__ void gemm_phase(LAS unsigned char* lds, const Gemm g, const StaticOrder S, const Epi E) {
;     ...
;         const bool has_next = S.next(ui + 1, nxt);
;         const char* nA = has_next ? (const char*)g.A + (size_t)nxt.pm * tstepA : cA; const char* nB = has_next ? (const char*)g.Bt + (size_t)nxt.pn * tstepB : cB;
;         for (int t = 0; t < nt; t += 2) {
;             const bool last = (t == nt - 2);
;             const char* a1 = cA + (size_t)(t + 1) * kstep;
;             const char* a2 = last ? nA : cA + (size_t)(t + 2) * kstep; const char* b2 = last ? nB : cB + (size_t)(t + 2) * kstep;
;             const char* a3 = a2 + kstep; const char* b3 = b2 + kstep;
;     ...
; #pragma unroll
;         for (int a = 0; a < 2; ++a)
; #pragma unroll
;             for (int b = 0; b < 2; ++b)
; #pragma unroll
;                 for (int m = 0; m < 4; ++m)
; #pragma unroll
;                     for (int n = 0; n < 2; ++n) acc[a][b][m][n] = (f32x4){0.f, 0.f, 0.f, 0.f};
;         cur = nxt; cA = nA; cB = nB; ++ui;
.LBB0_1323:
	s_ashr_i32 s45, s44, 31
	s_lshl_b64 s[46:47], s[44:45], 20
	s_add_u32 s46, s56, s46
	s_addc_u32 s47, s57, s47
	s_and_b64 s[48:49], s[36:37], exec
	s_cselect_b32 s45, s47, s51
	s_cselect_b32 s71, s46, s50
	s_ashr_i32 s43, s42, 31
	s_lshl_b64 s[48:49], s[42:43], 20
	v_readlane_b32 s43, v238, 42
	s_add_u32 s48, s43, s48
	v_readlane_b32 s43, v238, 43
	s_addc_u32 s49, s43, s49
	s_and_b64 s[54:55], s[36:37], exec
	s_cselect_b32 s43, s49, s53
	s_cselect_b32 s72, s48, s52
	s_add_u32 s50, s50, 0x80080
	s_addc_u32 s51, s51, 0
	s_add_u32 s73, s52, 0x100
	v_mov_b32_e32 v0, 0
	s_addc_u32 s74, s53, 0
	s_mov_b32 s75, -2
	v_mov_b32_e32 v1, v0
	v_mov_b32_e32 v2, v0
	v_mov_b32_e32 v3, v0
	v_mov_b32_e32 v4, v0
	v_mov_b32_e32 v5, v0
	v_mov_b32_e32 v6, v0
	v_mov_b32_e32 v7, v0
	v_mov_b32_e32 v8, v0
	v_mov_b32_e32 v9, v0
	v_mov_b32_e32 v10, v0
	v_mov_b32_e32 v11, v0
	v_mov_b32_e32 v12, v0
	v_mov_b32_e32 v13, v0
	v_mov_b32_e32 v14, v0
	v_mov_b32_e32 v15, v0
	v_mov_b32_e32 v16, v0
	v_mov_b32_e32 v17, v0
	v_mov_b32_e32 v18, v0
	v_mov_b32_e32 v19, v0
	v_mov_b32_e32 v20, v0
	v_mov_b32_e32 v21, v0
	v_mov_b32_e32 v22, v0
	v_mov_b32_e32 v23, v0
	v_mov_b32_e32 v24, v0
	v_mov_b32_e32 v25, v0
	v_mov_b32_e32 v26, v0
	v_mov_b32_e32 v27, v0
	v_mov_b32_e32 v28, v0
	v_mov_b32_e32 v29, v0
	v_mov_b32_e32 v30, v0
	v_mov_b32_e32 v31, v0
	v_mov_b32_e32 v40, v0
	v_mov_b32_e32 v41, v0
	v_mov_b32_e32 v42, v0
	v_mov_b32_e32 v43, v0
	v_mov_b32_e32 v44, v0
	v_mov_b32_e32 v45, v0
	v_mov_b32_e32 v46, v0
	v_mov_b32_e32 v47, v0
	v_mov_b32_e32 v56, v0
	v_mov_b32_e32 v57, v0
	v_mov_b32_e32 v58, v0
	v_mov_b32_e32 v59, v0
	v_mov_b32_e32 v64, v0
	v_mov_b32_e32 v65, v0
	v_mov_b32_e32 v66, v0
	v_mov_b32_e32 v67, v0
	v_mov_b32_e32 v76, v0
	v_mov_b32_e32 v77, v0
	v_mov_b32_e32 v78, v0
	v_mov_b32_e32 v79, v0
	v_mov_b32_e32 v84, v0
	v_mov_b32_e32 v85, v0
	v_mov_b32_e32 v86, v0
	v_mov_b32_e32 v87, v0
	v_mov_b32_e32 v88, v0
	v_mov_b32_e32 v89, v0
	v_mov_b32_e32 v90, v0
	v_mov_b32_e32 v91, v0
	v_mov_b32_e32 v92, v0
	v_mov_b32_e32 v93, v0
	v_mov_b32_e32 v94, v0
	v_mov_b32_e32 v95, v0
	v_mov_b32_e32 v32, v0
	v_mov_b32_e32 v33, v0
	v_mov_b32_e32 v34, v0
	v_mov_b32_e32 v35, v0
	v_mov_b32_e32 v36, v0
	v_mov_b32_e32 v37, v0
	v_mov_b32_e32 v38, v0
	v_mov_b32_e32 v39, v0
	v_mov_b32_e32 v48, v0
	v_mov_b32_e32 v49, v0
	v_mov_b32_e32 v50, v0
	v_mov_b32_e32 v51, v0
	v_mov_b32_e32 v52, v0
	v_mov_b32_e32 v53, v0
	v_mov_b32_e32 v54, v0
	v_mov_b32_e32 v55, v0
	v_mov_b32_e32 v60, v0
	v_mov_b32_e32 v61, v0
	v_mov_b32_e32 v62, v0
	v_mov_b32_e32 v63, v0
	v_mov_b32_e32 v68, v0
	v_mov_b32_e32 v69, v0
	v_mov_b32_e32 v70, v0
	v_mov_b32_e32 v71, v0
	v_mov_b32_e32 v72, v0
	v_mov_b32_e32 v73, v0
	v_mov_b32_e32 v74, v0
	v_mov_b32_e32 v75, v0
	v_mov_b32_e32 v80, v0
	v_mov_b32_e32 v81, v0
	v_mov_b32_e32 v82, v0
	v_mov_b32_e32 v83, v0
	v_mov_b32_e32 v96, v0
	v_mov_b32_e32 v97, v0
	v_mov_b32_e32 v98, v0
	v_mov_b32_e32 v99, v0
	v_mov_b32_e32 v100, v0
	v_mov_b32_e32 v101, v0
	v_mov_b32_e32 v102, v0
	v_mov_b32_e32 v103, v0
	v_mov_b32_e32 v104, v0
	v_mov_b32_e32 v105, v0
	v_mov_b32_e32 v106, v0
	v_mov_b32_e32 v107, v0
	v_mov_b32_e32 v108, v0
	v_mov_b32_e32 v109, v0
	v_mov_b32_e32 v110, v0
	v_mov_b32_e32 v111, v0
	v_mov_b32_e32 v112, v0
	v_mov_b32_e32 v113, v0
	v_mov_b32_e32 v114, v0
	v_mov_b32_e32 v115, v0
	v_mov_b32_e32 v116, v0
	v_mov_b32_e32 v117, v0
	v_mov_b32_e32 v118, v0
	v_mov_b32_e32 v119, v0
	v_mov_b32_e32 v120, v0
	v_mov_b32_e32 v121, v0
	v_mov_b32_e32 v122, v0
	v_mov_b32_e32 v123, v0
	v_mov_b32_e32 v124, v0
	v_mov_b32_e32 v125, v0
	v_mov_b32_e32 v126, v0
	v_mov_b32_e32 v127, v0
	.p2align 6

; template <class Epi, bool ALIGN_EPI = PG8_ALIGN>
; __device__ __forceinline__ void gemm_phase(LAS unsigned char* lds, const Gemm g, const StaticOrder S, const Epi E) {
;     ...
;         const bool has_next = S.next(ui + 1, nxt);
;         const char* nA = has_next ? (const char*)g.A + (size_t)nxt.pm * tstepA : cA; const char* nB = has_next ? (const char*)g.Bt + (size_t)nxt.pn * tstepB : cB;
;         for (int t = 0; t < nt; t += 2) {
;             const bool last = (t == nt - 2);
;             const char* a1 = cA + (size_t)(t + 1) * kstep;
;             const char* a2 = last ? nA : cA + (size_t)(t + 2) * kstep; const char* b2 = last ? nB : cB + (size_t)(t + 2) * kstep;
;             const char* a3 = a2 + kstep; const char* b3 = b2 + kstep;
;     ...
; #pragma unroll
;         for (int a = 0; a < 2; ++a)
; #pragma unroll
;             for (int b = 0; b < 2; ++b)
; #pragma unroll
;                 for (int m = 0; m < 4; ++m)
; #pragma unroll
;                     for (int n = 0; n < 2; ++n) acc[a][b][m][n] = (f32x4){0.f, 0.f, 0.f, 0.f};
;         cur = nxt; cA = nA; cB = nB; ++ui;
.LBB0_1347:
	s_ashr_i32 s45, s44, 31
	s_lshl_b64 s[46:47], s[44:45], 20
	s_add_u32 s46, s17, s46
	s_addc_u32 s47, s33, s47
	s_and_b64 s[48:49], s[36:37], exec
	s_cselect_b32 s45, s47, s51
	s_cselect_b32 s71, s46, s50
	s_ashr_i32 s43, s42, 31
	s_lshl_b64 s[48:49], s[42:43], 20
	s_add_u32 s48, s56, s48
	s_addc_u32 s49, s57, s49
	s_and_b64 s[54:55], s[36:37], exec
	s_cselect_b32 s43, s49, s53
	s_cselect_b32 s72, s48, s52
	s_add_u32 s50, s50, 0x80080
	s_addc_u32 s51, s51, 0
	s_add_u32 s73, s52, 0x100
	v_mov_b32_e32 v0, 0
	s_addc_u32 s74, s53, 0
	s_mov_b32 s75, -2
	v_mov_b32_e32 v1, v0
	v_mov_b32_e32 v2, v0
	v_mov_b32_e32 v3, v0
	v_mov_b32_e32 v4, v0
	v_mov_b32_e32 v5, v0
	v_mov_b32_e32 v6, v0
	v_mov_b32_e32 v7, v0
	v_mov_b32_e32 v8, v0
	v_mov_b32_e32 v9, v0
	v_mov_b32_e32 v10, v0
	v_mov_b32_e32 v11, v0
	v_mov_b32_e32 v12, v0
	v_mov_b32_e32 v13, v0
	v_mov_b32_e32 v14, v0
	v_mov_b32_e32 v15, v0
	v_mov_b32_e32 v16, v0
	v_mov_b32_e32 v17, v0
	v_mov_b32_e32 v18, v0
	v_mov_b32_e32 v19, v0
	v_mov_b32_e32 v20, v0
	v_mov_b32_e32 v21, v0
	v_mov_b32_e32 v22, v0
	v_mov_b32_e32 v23, v0
	v_mov_b32_e32 v24, v0
	v_mov_b32_e32 v25, v0
	v_mov_b32_e32 v26, v0
	v_mov_b32_e32 v27, v0
	v_mov_b32_e32 v28, v0
	v_mov_b32_e32 v29, v0
	v_mov_b32_e32 v30, v0
	v_mov_b32_e32 v31, v0
	v_mov_b32_e32 v40, v0
	v_mov_b32_e32 v41, v0
	v_mov_b32_e32 v42, v0
	v_mov_b32_e32 v43, v0
	v_mov_b32_e32 v44, v0
	v_mov_b32_e32 v45, v0
	v_mov_b32_e32 v46, v0
	v_mov_b32_e32 v47, v0
	v_mov_b32_e32 v56, v0
	v_mov_b32_e32 v57, v0
	v_mov_b32_e32 v58, v0
	v_mov_b32_e32 v59, v0
	v_mov_b32_e32 v64, v0
	v_mov_b32_e32 v65, v0
	v_mov_b32_e32 v66, v0
	v_mov_b32_e32 v67, v0
	v_mov_b32_e32 v76, v0
	v_mov_b32_e32 v77, v0
	v_mov_b32_e32 v78, v0
	v_mov_b32_e32 v79, v0
	v_mov_b32_e32 v84, v0
	v_mov_b32_e32 v85, v0
	v_mov_b32_e32 v86, v0
	v_mov_b32_e32 v87, v0
	v_mov_b32_e32 v88, v0
	v_mov_b32_e32 v89, v0
	v_mov_b32_e32 v90, v0
	v_mov_b32_e32 v91, v0
	v_mov_b32_e32 v92, v0
	v_mov_b32_e32 v93, v0
	v_mov_b32_e32 v94, v0
	v_mov_b32_e32 v95, v0
	v_mov_b32_e32 v32, v0
	v_mov_b32_e32 v33, v0
	v_mov_b32_e32 v34, v0
	v_mov_b32_e32 v35, v0
	v_mov_b32_e32 v36, v0
	v_mov_b32_e32 v37, v0
	v_mov_b32_e32 v38, v0
	v_mov_b32_e32 v39, v0
	v_mov_b32_e32 v48, v0
	v_mov_b32_e32 v49, v0
	v_mov_b32_e32 v50, v0
	v_mov_b32_e32 v51, v0
	v_mov_b32_e32 v52, v0
	v_mov_b32_e32 v53, v0
	v_mov_b32_e32 v54, v0
	v_mov_b32_e32 v55, v0
	v_mov_b32_e32 v60, v0
	v_mov_b32_e32 v61, v0
	v_mov_b32_e32 v62, v0
	v_mov_b32_e32 v63, v0
	v_mov_b32_e32 v68, v0
	v_mov_b32_e32 v69, v0
	v_mov_b32_e32 v70, v0
	v_mov_b32_e32 v71, v0
	v_mov_b32_e32 v72, v0
	v_mov_b32_e32 v73, v0
	v_mov_b32_e32 v74, v0
	v_mov_b32_e32 v75, v0
	v_mov_b32_e32 v80, v0
	v_mov_b32_e32 v81, v0
	v_mov_b32_e32 v82, v0
	v_mov_b32_e32 v83, v0
	v_mov_b32_e32 v96, v0
	v_mov_b32_e32 v97, v0
	v_mov_b32_e32 v98, v0
	v_mov_b32_e32 v99, v0
	v_mov_b32_e32 v100, v0
	v_mov_b32_e32 v101, v0
	v_mov_b32_e32 v102, v0
	v_mov_b32_e32 v103, v0
	v_mov_b32_e32 v104, v0
	v_mov_b32_e32 v105, v0
	v_mov_b32_e32 v106, v0
	v_mov_b32_e32 v107, v0
	v_mov_b32_e32 v108, v0
	v_mov_b32_e32 v109, v0
	v_mov_b32_e32 v110, v0
	v_mov_b32_e32 v111, v0
	v_mov_b32_e32 v112, v0
	v_mov_b32_e32 v113, v0
	v_mov_b32_e32 v114, v0
	v_mov_b32_e32 v115, v0
	v_mov_b32_e32 v116, v0
	v_mov_b32_e32 v117, v0
	v_mov_b32_e32 v118, v0
	v_mov_b32_e32 v119, v0
	v_mov_b32_e32 v120, v0
	v_mov_b32_e32 v121, v0
	v_mov_b32_e32 v122, v0
	v_mov_b32_e32 v123, v0
	v_mov_b32_e32 v124, v0
	v_mov_b32_e32 v125, v0
	v_mov_b32_e32 v126, v0
	v_mov_b32_e32 v127, v0
	.p2align 6

; template <class Epi, bool ALIGN_EPI = PG8_ALIGN>
; __device__ __forceinline__ void gemm_phase(LAS unsigned char* lds, const Gemm g, const StaticOrder S, const Epi E) {
;     ...
;         const bool has_next = S.next(ui + 1, nxt);
;         const char* nA = has_next ? (const char*)g.A + (size_t)nxt.pm * tstepA : cA; const char* nB = has_next ? (const char*)g.Bt + (size_t)nxt.pn * tstepB : cB;
;         for (int t = 0; t < nt; t += 2) {
;             const bool last = (t == nt - 2);
;             const char* a1 = cA + (size_t)(t + 1) * kstep;
;             const char* a2 = last ? nA : cA + (size_t)(t + 2) * kstep; const char* b2 = last ? nB : cB + (size_t)(t + 2) * kstep;
;             const char* a3 = a2 + kstep; const char* b3 = b2 + kstep;
;     ...
; #pragma unroll
;         for (int a = 0; a < 2; ++a)
; #pragma unroll
;             for (int b = 0; b < 2; ++b)
; #pragma unroll
;                 for (int m = 0; m < 4; ++m)
; #pragma unroll
;                     for (int n = 0; n < 2; ++n) acc[a][b][m][n] = (f32x4){0.f, 0.f, 0.f, 0.f};
;         cur = nxt; cA = nA; cB = nB; ++ui;
.LBB0_1601:
	s_ashr_i32 s23, s22, 31
	s_lshl_b64 s[16:17], s[22:23], 18
	s_add_u32 s24, s64, s16
	s_addc_u32 s25, s65, s17
	s_and_b64 s[16:17], s[4:5], exec
	s_cselect_b32 s13, s25, s37
	s_cselect_b32 s14, s24, s36
	s_ashr_i32 s21, s20, 31
	s_lshl_b64 s[16:17], s[20:21], 18
	s_add_u32 s26, s58, s16
	s_addc_u32 s27, s59, s17
	s_and_b64 s[16:17], s[4:5], exec
	s_cselect_b32 s16, s27, s39
	s_cselect_b32 s17, s26, s38
	s_add_u32 s36, s36, 0x20080
	s_addc_u32 s37, s37, 0
	s_add_u32 s21, s38, 0x100
	v_mov_b32_e32 v0, 0
	s_addc_u32 s23, s39, 0
	s_mov_b32 s33, -2
	v_mov_b32_e32 v1, v0
	v_mov_b32_e32 v2, v0
	v_mov_b32_e32 v3, v0
	v_mov_b32_e32 v4, v0
	v_mov_b32_e32 v5, v0
	v_mov_b32_e32 v6, v0
	v_mov_b32_e32 v7, v0
	v_mov_b32_e32 v16, v0
	v_mov_b32_e32 v17, v0
	v_mov_b32_e32 v18, v0
	v_mov_b32_e32 v19, v0
	v_mov_b32_e32 v20, v0
	v_mov_b32_e32 v21, v0
	v_mov_b32_e32 v22, v0
	v_mov_b32_e32 v23, v0
	v_mov_b32_e32 v32, v0
	v_mov_b32_e32 v33, v0
	v_mov_b32_e32 v34, v0
	v_mov_b32_e32 v35, v0
	v_mov_b32_e32 v36, v0
	v_mov_b32_e32 v37, v0
	v_mov_b32_e32 v38, v0
	v_mov_b32_e32 v39, v0
	v_mov_b32_e32 v48, v0
	v_mov_b32_e32 v49, v0
	v_mov_b32_e32 v50, v0
	v_mov_b32_e32 v51, v0
	v_mov_b32_e32 v52, v0
	v_mov_b32_e32 v53, v0
	v_mov_b32_e32 v54, v0
	v_mov_b32_e32 v55, v0
	v_mov_b32_e32 v8, v0
	v_mov_b32_e32 v9, v0
	v_mov_b32_e32 v10, v0
	v_mov_b32_e32 v11, v0
	v_mov_b32_e32 v12, v0
	v_mov_b32_e32 v13, v0
	v_mov_b32_e32 v14, v0
	v_mov_b32_e32 v15, v0
	v_mov_b32_e32 v24, v0
	v_mov_b32_e32 v25, v0
	v_mov_b32_e32 v26, v0
	v_mov_b32_e32 v27, v0
	v_mov_b32_e32 v28, v0
	v_mov_b32_e32 v29, v0
	v_mov_b32_e32 v30, v0
	v_mov_b32_e32 v31, v0
	v_mov_b32_e32 v40, v0
	v_mov_b32_e32 v41, v0
	v_mov_b32_e32 v42, v0
	v_mov_b32_e32 v43, v0
	v_mov_b32_e32 v44, v0
	v_mov_b32_e32 v45, v0
	v_mov_b32_e32 v46, v0
	v_mov_b32_e32 v47, v0
	v_mov_b32_e32 v56, v0
	v_mov_b32_e32 v57, v0
	v_mov_b32_e32 v58, v0
	v_mov_b32_e32 v59, v0
	v_mov_b32_e32 v60, v0
	v_mov_b32_e32 v61, v0
	v_mov_b32_e32 v62, v0
	v_mov_b32_e32 v63, v0
	v_mov_b32_e32 v64, v0
	v_mov_b32_e32 v65, v0
	v_mov_b32_e32 v66, v0
	v_mov_b32_e32 v67, v0
	v_mov_b32_e32 v68, v0
	v_mov_b32_e32 v69, v0
	v_mov_b32_e32 v70, v0
	v_mov_b32_e32 v71, v0
	v_mov_b32_e32 v80, v0
	v_mov_b32_e32 v81, v0
	v_mov_b32_e32 v82, v0
	v_mov_b32_e32 v83, v0
	v_mov_b32_e32 v84, v0
	v_mov_b32_e32 v85, v0
	v_mov_b32_e32 v86, v0
	v_mov_b32_e32 v87, v0
	v_mov_b32_e32 v96, v0
	v_mov_b32_e32 v97, v0
	v_mov_b32_e32 v98, v0
	v_mov_b32_e32 v99, v0
	v_mov_b32_e32 v100, v0
	v_mov_b32_e32 v101, v0
	v_mov_b32_e32 v102, v0
	v_mov_b32_e32 v103, v0
	v_mov_b32_e32 v112, v0
	v_mov_b32_e32 v113, v0
	v_mov_b32_e32 v114, v0
	v_mov_b32_e32 v115, v0
	v_mov_b32_e32 v116, v0
	v_mov_b32_e32 v117, v0
	v_mov_b32_e32 v118, v0
	v_mov_b32_e32 v119, v0
	v_mov_b32_e32 v72, v0
	v_mov_b32_e32 v73, v0
	v_mov_b32_e32 v74, v0
	v_mov_b32_e32 v75, v0
	v_mov_b32_e32 v76, v0
	v_mov_b32_e32 v77, v0
	v_mov_b32_e32 v78, v0
	v_mov_b32_e32 v79, v0
	v_mov_b32_e32 v88, v0
	v_mov_b32_e32 v89, v0
	v_mov_b32_e32 v90, v0
	v_mov_b32_e32 v91, v0
	v_mov_b32_e32 v92, v0
	v_mov_b32_e32 v93, v0
	v_mov_b32_e32 v94, v0
	v_mov_b32_e32 v95, v0
	v_mov_b32_e32 v104, v0
	v_mov_b32_e32 v105, v0
	v_mov_b32_e32 v106, v0
	v_mov_b32_e32 v107, v0
	v_mov_b32_e32 v108, v0
	v_mov_b32_e32 v109, v0
	v_mov_b32_e32 v110, v0
	v_mov_b32_e32 v111, v0
	v_mov_b32_e32 v120, v0
	v_mov_b32_e32 v121, v0
	v_mov_b32_e32 v122, v0
	v_mov_b32_e32 v123, v0
	v_mov_b32_e32 v124, v0
	v_mov_b32_e32 v125, v0
	v_mov_b32_e32 v126, v0
	v_mov_b32_e32 v127, v0
	.p2align 6

; template <class Epi, bool ALIGN_EPI = PG8_ALIGN>
; __device__ __forceinline__ void gemm_phase(LAS unsigned char* lds, const Gemm g, const StaticOrder S, const Epi E) {
;     ...
;         const bool has_next = S.next(ui + 1, nxt);
;         const char* nA = has_next ? (const char*)g.A + (size_t)nxt.pm * tstepA : cA; const char* nB = has_next ? (const char*)g.Bt + (size_t)nxt.pn * tstepB : cB;
;         for (int t = 0; t < nt; t += 2) {
;             const bool last = (t == nt - 2);
;             const char* a1 = cA + (size_t)(t + 1) * kstep;
;             const char* a2 = last ? nA : cA + (size_t)(t + 2) * kstep; const char* b2 = last ? nB : cB + (size_t)(t + 2) * kstep;
;             const char* a3 = a2 + kstep; const char* b3 = b2 + kstep;
;     ...
; #pragma unroll
;         for (int a = 0; a < 2; ++a)
; #pragma unroll
;             for (int b = 0; b < 2; ++b)
; #pragma unroll
;                 for (int m = 0; m < 4; ++m)
; #pragma unroll
;                     for (int n = 0; n < 2; ++n) acc[a][b][m][n] = (f32x4){0.f, 0.f, 0.f, 0.f};
;         cur = nxt; cA = nA; cB = nB; ++ui;
.LBB0_1688:
	s_ashr_i32 s23, s22, 31
	s_lshl_b64 s[24:25], s[22:23], 20
	s_add_u32 s24, s40, s24
	s_addc_u32 s25, s41, s25
	s_and_b64 s[26:27], s[2:3], exec
	s_cselect_b32 s14, s25, s13
	s_cselect_b32 s23, s24, s12
	s_ashr_i32 s21, s20, 31
	s_lshl_b64 s[26:27], s[20:21], 20
	s_add_u32 s26, s86, s26
	s_addc_u32 s27, s87, s27
	s_and_b64 s[36:37], s[2:3], exec
	s_cselect_b32 s21, s27, s29
	s_cselect_b32 s50, s26, s28
	s_add_u32 s12, s12, 0x80080
	s_addc_u32 s13, s13, 0
	s_add_u32 s51, s28, 0x100
	v_mov_b32_e32 v0, 0
	s_addc_u32 s52, s29, 0
	s_mov_b32 s53, -2
	v_mov_b32_e32 v1, v0
	v_mov_b32_e32 v2, v0
	v_mov_b32_e32 v3, v0
	v_mov_b32_e32 v4, v0
	v_mov_b32_e32 v5, v0
	v_mov_b32_e32 v6, v0
	v_mov_b32_e32 v7, v0
	v_mov_b32_e32 v16, v0
	v_mov_b32_e32 v17, v0
	v_mov_b32_e32 v18, v0
	v_mov_b32_e32 v19, v0
	v_mov_b32_e32 v20, v0
	v_mov_b32_e32 v21, v0
	v_mov_b32_e32 v22, v0
	v_mov_b32_e32 v23, v0
	v_mov_b32_e32 v32, v0
	v_mov_b32_e32 v33, v0
	v_mov_b32_e32 v34, v0
	v_mov_b32_e32 v35, v0
	v_mov_b32_e32 v36, v0
	v_mov_b32_e32 v37, v0
	v_mov_b32_e32 v38, v0
	v_mov_b32_e32 v39, v0
	v_mov_b32_e32 v48, v0
	v_mov_b32_e32 v49, v0
	v_mov_b32_e32 v50, v0
	v_mov_b32_e32 v51, v0
	v_mov_b32_e32 v52, v0
	v_mov_b32_e32 v53, v0
	v_mov_b32_e32 v54, v0
	v_mov_b32_e32 v55, v0
	v_mov_b32_e32 v8, v0
	v_mov_b32_e32 v9, v0
	v_mov_b32_e32 v10, v0
	v_mov_b32_e32 v11, v0
	v_mov_b32_e32 v12, v0
	v_mov_b32_e32 v13, v0
	v_mov_b32_e32 v14, v0
	v_mov_b32_e32 v15, v0
	v_mov_b32_e32 v24, v0
	v_mov_b32_e32 v25, v0
	v_mov_b32_e32 v26, v0
	v_mov_b32_e32 v27, v0
	v_mov_b32_e32 v28, v0
	v_mov_b32_e32 v29, v0
	v_mov_b32_e32 v30, v0
	v_mov_b32_e32 v31, v0
	v_mov_b32_e32 v40, v0
	v_mov_b32_e32 v41, v0
	v_mov_b32_e32 v42, v0
	v_mov_b32_e32 v43, v0
	v_mov_b32_e32 v44, v0
	v_mov_b32_e32 v45, v0
	v_mov_b32_e32 v46, v0
	v_mov_b32_e32 v47, v0
	v_mov_b32_e32 v56, v0
	v_mov_b32_e32 v57, v0
	v_mov_b32_e32 v58, v0
	v_mov_b32_e32 v59, v0
	v_mov_b32_e32 v60, v0
	v_mov_b32_e32 v61, v0
	v_mov_b32_e32 v62, v0
	v_mov_b32_e32 v63, v0
	v_mov_b32_e32 v64, v0
	v_mov_b32_e32 v65, v0
	v_mov_b32_e32 v66, v0
	v_mov_b32_e32 v67, v0
	v_mov_b32_e32 v68, v0
	v_mov_b32_e32 v69, v0
	v_mov_b32_e32 v70, v0
	v_mov_b32_e32 v71, v0
	v_mov_b32_e32 v80, v0
	v_mov_b32_e32 v81, v0
	v_mov_b32_e32 v82, v0
	v_mov_b32_e32 v83, v0
	v_mov_b32_e32 v84, v0
	v_mov_b32_e32 v85, v0
	v_mov_b32_e32 v86, v0
	v_mov_b32_e32 v87, v0
	v_mov_b32_e32 v96, v0
	v_mov_b32_e32 v97, v0
	v_mov_b32_e32 v98, v0
	v_mov_b32_e32 v99, v0
	v_mov_b32_e32 v100, v0
	v_mov_b32_e32 v101, v0
	v_mov_b32_e32 v102, v0
	v_mov_b32_e32 v103, v0
	v_mov_b32_e32 v112, v0
	v_mov_b32_e32 v113, v0
	v_mov_b32_e32 v114, v0
	v_mov_b32_e32 v115, v0
	v_mov_b32_e32 v116, v0
	v_mov_b32_e32 v117, v0
	v_mov_b32_e32 v118, v0
	v_mov_b32_e32 v119, v0
	v_mov_b32_e32 v72, v0
	v_mov_b32_e32 v73, v0
	v_mov_b32_e32 v74, v0
	v_mov_b32_e32 v75, v0
	v_mov_b32_e32 v76, v0
	v_mov_b32_e32 v77, v0
	v_mov_b32_e32 v78, v0
	v_mov_b32_e32 v79, v0
	v_mov_b32_e32 v88, v0
	v_mov_b32_e32 v89, v0
	v_mov_b32_e32 v90, v0
	v_mov_b32_e32 v91, v0
	v_mov_b32_e32 v92, v0
	v_mov_b32_e32 v93, v0
	v_mov_b32_e32 v94, v0
	v_mov_b32_e32 v95, v0
	v_mov_b32_e32 v104, v0
	v_mov_b32_e32 v105, v0
	v_mov_b32_e32 v106, v0
	v_mov_b32_e32 v107, v0
	v_mov_b32_e32 v108, v0
	v_mov_b32_e32 v109, v0
	v_mov_b32_e32 v110, v0
	v_mov_b32_e32 v111, v0
	v_mov_b32_e32 v120, v0
	v_mov_b32_e32 v121, v0
	v_mov_b32_e32 v122, v0
	v_mov_b32_e32 v123, v0
	v_mov_b32_e32 v124, v0
	v_mov_b32_e32 v125, v0
	v_mov_b32_e32 v126, v0
	v_mov_b32_e32 v127, v0
	.p2align 6

; template <class Epi, bool ALIGN_EPI = PG8_ALIGN>
; __device__ __forceinline__ void gemm_phase(LAS unsigned char* lds, const Gemm g, const StaticOrder S, const Epi E) {
;     ...
;         const bool has_next = S.next(ui + 1, nxt);
;         const char* nA = has_next ? (const char*)g.A + (size_t)nxt.pm * tstepA : cA; const char* nB = has_next ? (const char*)g.Bt + (size_t)nxt.pn * tstepB : cB;
;         for (int t = 0; t < nt; t += 2) {
;             const bool last = (t == nt - 2);
;             const char* a1 = cA + (size_t)(t + 1) * kstep;
;             const char* a2 = last ? nA : cA + (size_t)(t + 2) * kstep; const char* b2 = last ? nB : cB + (size_t)(t + 2) * kstep;
;             const char* a3 = a2 + kstep; const char* b3 = b2 + kstep;
;     ...
; #pragma unroll
;         for (int a = 0; a < 2; ++a)
; #pragma unroll
;             for (int b = 0; b < 2; ++b)
; #pragma unroll
;                 for (int m = 0; m < 4; ++m)
; #pragma unroll
;                     for (int n = 0; n < 2; ++n) acc[a][b][m][n] = (f32x4){0.f, 0.f, 0.f, 0.f};
;         cur = nxt; cA = nA; cB = nB; ++ui;
.LBB0_1771:
	s_add_u32 s24, s24, 0x160080
	s_addc_u32 s25, s25, 0
	s_add_u32 s50, s26, 0x100
	v_mov_b32_e32 v0, 0
	s_addc_u32 s51, s27, 0
	s_mov_b32 s52, -2
	v_mov_b32_e32 v1, v0
	v_mov_b32_e32 v2, v0
	v_mov_b32_e32 v3, v0
	v_mov_b32_e32 v4, v0
	v_mov_b32_e32 v5, v0
	v_mov_b32_e32 v6, v0
	v_mov_b32_e32 v7, v0
	v_mov_b32_e32 v16, v0
	v_mov_b32_e32 v17, v0
	v_mov_b32_e32 v18, v0
	v_mov_b32_e32 v19, v0
	v_mov_b32_e32 v20, v0
	v_mov_b32_e32 v21, v0
	v_mov_b32_e32 v22, v0
	v_mov_b32_e32 v23, v0
	v_mov_b32_e32 v32, v0
	v_mov_b32_e32 v33, v0
	v_mov_b32_e32 v34, v0
	v_mov_b32_e32 v35, v0
	v_mov_b32_e32 v36, v0
	v_mov_b32_e32 v37, v0
	v_mov_b32_e32 v38, v0
	v_mov_b32_e32 v39, v0
	v_mov_b32_e32 v48, v0
	v_mov_b32_e32 v49, v0
	v_mov_b32_e32 v50, v0
	v_mov_b32_e32 v51, v0
	v_mov_b32_e32 v52, v0
	v_mov_b32_e32 v53, v0
	v_mov_b32_e32 v54, v0
	v_mov_b32_e32 v55, v0
	v_mov_b32_e32 v8, v0
	v_mov_b32_e32 v9, v0
	v_mov_b32_e32 v10, v0
	v_mov_b32_e32 v11, v0
	v_mov_b32_e32 v12, v0
	v_mov_b32_e32 v13, v0
	v_mov_b32_e32 v14, v0
	v_mov_b32_e32 v15, v0
	v_mov_b32_e32 v24, v0
	v_mov_b32_e32 v25, v0
	v_mov_b32_e32 v26, v0
	v_mov_b32_e32 v27, v0
	v_mov_b32_e32 v28, v0
	v_mov_b32_e32 v29, v0
	v_mov_b32_e32 v30, v0
	v_mov_b32_e32 v31, v0
	v_mov_b32_e32 v40, v0
	v_mov_b32_e32 v41, v0
	v_mov_b32_e32 v42, v0
	v_mov_b32_e32 v43, v0
	v_mov_b32_e32 v44, v0
	v_mov_b32_e32 v45, v0
	v_mov_b32_e32 v46, v0
	v_mov_b32_e32 v47, v0
	v_mov_b32_e32 v56, v0
	v_mov_b32_e32 v57, v0
	v_mov_b32_e32 v58, v0
	v_mov_b32_e32 v59, v0
	v_mov_b32_e32 v60, v0
	v_mov_b32_e32 v61, v0
	v_mov_b32_e32 v62, v0
	v_mov_b32_e32 v63, v0
	v_mov_b32_e32 v64, v0
	v_mov_b32_e32 v65, v0
	v_mov_b32_e32 v66, v0
	v_mov_b32_e32 v67, v0
	v_mov_b32_e32 v68, v0
	v_mov_b32_e32 v69, v0
	v_mov_b32_e32 v70, v0
	v_mov_b32_e32 v71, v0
	v_mov_b32_e32 v80, v0
	v_mov_b32_e32 v81, v0
	v_mov_b32_e32 v82, v0
	v_mov_b32_e32 v83, v0
	v_mov_b32_e32 v84, v0
	v_mov_b32_e32 v85, v0
	v_mov_b32_e32 v86, v0
	v_mov_b32_e32 v87, v0
	v_mov_b32_e32 v96, v0
	v_mov_b32_e32 v97, v0
	v_mov_b32_e32 v98, v0
	v_mov_b32_e32 v99, v0
	v_mov_b32_e32 v100, v0
	v_mov_b32_e32 v101, v0
	v_mov_b32_e32 v102, v0
	v_mov_b32_e32 v103, v0
	v_mov_b32_e32 v112, v0
	v_mov_b32_e32 v113, v0
	v_mov_b32_e32 v114, v0
	v_mov_b32_e32 v115, v0
	v_mov_b32_e32 v116, v0
	v_mov_b32_e32 v117, v0
	v_mov_b32_e32 v118, v0
	v_mov_b32_e32 v119, v0
	v_mov_b32_e32 v72, v0
	v_mov_b32_e32 v73, v0
	v_mov_b32_e32 v74, v0
	v_mov_b32_e32 v75, v0
	v_mov_b32_e32 v76, v0
	v_mov_b32_e32 v77, v0
	v_mov_b32_e32 v78, v0
	v_mov_b32_e32 v79, v0
	v_mov_b32_e32 v88, v0
	v_mov_b32_e32 v89, v0
	v_mov_b32_e32 v90, v0
	v_mov_b32_e32 v91, v0
	v_mov_b32_e32 v92, v0
	v_mov_b32_e32 v93, v0
	v_mov_b32_e32 v94, v0
	v_mov_b32_e32 v95, v0
	v_mov_b32_e32 v104, v0
	v_mov_b32_e32 v105, v0
	v_mov_b32_e32 v106, v0
	v_mov_b32_e32 v107, v0
	v_mov_b32_e32 v108, v0
	v_mov_b32_e32 v109, v0
	v_mov_b32_e32 v110, v0
	v_mov_b32_e32 v111, v0
	v_mov_b32_e32 v120, v0
	v_mov_b32_e32 v121, v0
	v_mov_b32_e32 v122, v0
	v_mov_b32_e32 v123, v0
	v_mov_b32_e32 v124, v0
	v_mov_b32_e32 v125, v0
	v_mov_b32_e32 v126, v0
	v_mov_b32_e32 v127, v0
	.p2align 6
